# v7: GU K-loop LDS-DMA stage loads rebalanced 4/4 per load segment + counted vmcnt(4); s_setprio moved off the barrier hand-off path; QKV epilogue rotary-table loads double-buffered two rows ahead with
# speedup vs baseline: 1.0080x; 1.0080x over previous
.LBB0_189:
	s_add_u32 s30, s28, 0xfff80080
	s_addc_u32 s31, s29, -1
	s_add_i32 s67, 0, 0x10000
	s_cmp_eq_u32 s66, 28
	s_cselect_b32 s35, s21, s31
	s_cselect_b32 s34, s42, s30
	s_cselect_b32 s31, s19, s63
	s_cselect_b32 s30, s43, s62
	s_add_i32 s70, 0, 0x14000
	v_add_u32_e32 v84, s67, v181
	v_add_u32_e32 v156, s70, v181
	ds_read_b128 v[64:67], v84
	ds_read_b128 v[72:75], v84 offset:1024
	ds_read_b128 v[80:83], v84 offset:2048
	ds_read_b128 v[84:87], v84 offset:3072
	ds_read_b128 v[144:147], v156
	ds_read_b128 v[148:151], v156 offset:1024
	ds_read_b128 v[152:155], v156 offset:2048
	ds_read_b128 v[156:159], v156 offset:3072
	v_lshl_add_u64 v[212:213], s[28:29], 0, v[168:169]
	s_add_i32 m0, s27, 0xc000
	ds_read_b128 v[172:175], v182
	ds_read_b128 v[176:179], v182 offset:1024
	ds_read_b128 v[184:187], v182 offset:2048
	ds_read_b128 v[188:191], v182 offset:3072
	ds_read_b128 v[192:195], v182 offset:4096
	ds_read_b128 v[196:199], v182 offset:5120
	ds_read_b128 v[202:205], v182 offset:6144
	ds_read_b128 v[206:209], v182 offset:7168
	global_load_lds_dwordx4 v[212:213], off
	v_lshl_add_u64 v[212:213], s[28:29], 0, v[170:171]
	s_add_i32 m0, s27, 0xe000
	s_nop 0
	global_load_lds_dwordx4 v[212:213], off
	s_waitcnt vmcnt(8)
	s_waitcnt lgkmcnt(0)
	s_setprio 1
	s_barrier
	v_mfma_f32_16x16x32_bf16 v[140:143], v[64:67], v[172:175], v[140:143]
	v_mfma_f32_16x16x32_bf16 v[136:139], v[80:83], v[172:175], v[136:139]
	v_mfma_f32_16x16x32_bf16 v[124:127], v[64:67], v[184:187], v[124:127]
	v_mfma_f32_16x16x32_bf16 v[120:123], v[80:83], v[184:187], v[120:123]
	v_mfma_f32_16x16x32_bf16 v[108:111], v[64:67], v[192:195], v[108:111]
	v_mfma_f32_16x16x32_bf16 v[104:107], v[80:83], v[192:195], v[104:107]
	v_mfma_f32_16x16x32_bf16 v[92:95], v[64:67], v[202:205], v[92:95]
	v_mfma_f32_16x16x32_bf16 v[88:91], v[80:83], v[202:205], v[88:91]
	v_mfma_f32_16x16x32_bf16 v[140:143], v[72:75], v[176:179], v[140:143]
	v_mfma_f32_16x16x32_bf16 v[136:139], v[84:87], v[176:179], v[136:139]
	v_mfma_f32_16x16x32_bf16 v[124:127], v[72:75], v[188:191], v[124:127]
	v_mfma_f32_16x16x32_bf16 v[120:123], v[84:87], v[188:191], v[120:123]
	v_mfma_f32_16x16x32_bf16 v[108:111], v[72:75], v[196:199], v[108:111]
	v_mfma_f32_16x16x32_bf16 v[104:107], v[84:87], v[196:199], v[104:107]
	v_mfma_f32_16x16x32_bf16 v[92:95], v[72:75], v[206:209], v[92:95]
	v_mfma_f32_16x16x32_bf16 v[88:91], v[84:87], v[206:209], v[88:91]
	s_setprio 0
	s_setprio 1
	v_mfma_f32_16x16x32_bf16 v[132:135], v[144:147], v[172:175], v[132:135]
	v_mfma_f32_16x16x32_bf16 v[128:131], v[152:155], v[172:175], v[128:131]
	v_mfma_f32_16x16x32_bf16 v[116:119], v[144:147], v[184:187], v[116:119]
	v_mfma_f32_16x16x32_bf16 v[112:115], v[152:155], v[184:187], v[112:115]
	v_mfma_f32_16x16x32_bf16 v[100:103], v[144:147], v[192:195], v[100:103]
	v_mfma_f32_16x16x32_bf16 v[96:99], v[152:155], v[192:195], v[96:99]
	v_mfma_f32_16x16x32_bf16 v[76:79], v[144:147], v[202:205], v[76:79]
	v_mfma_f32_16x16x32_bf16 v[68:71], v[152:155], v[202:205], v[68:71]
	v_mfma_f32_16x16x32_bf16 v[132:135], v[148:151], v[176:179], v[132:135]
	v_mfma_f32_16x16x32_bf16 v[128:131], v[156:159], v[176:179], v[128:131]
	v_mfma_f32_16x16x32_bf16 v[116:119], v[148:151], v[188:191], v[116:119]
	v_mfma_f32_16x16x32_bf16 v[112:115], v[156:159], v[188:191], v[112:115]
	v_mfma_f32_16x16x32_bf16 v[100:103], v[148:151], v[196:199], v[100:103]
	v_mfma_f32_16x16x32_bf16 v[96:99], v[156:159], v[196:199], v[96:99]
	v_mfma_f32_16x16x32_bf16 v[76:79], v[148:151], v[206:209], v[76:79]
	v_mfma_f32_16x16x32_bf16 v[68:71], v[156:159], v[206:209], v[68:71]
	s_barrier
	s_setprio 0
	s_add_i32 s67, s67, s41
	v_lshl_add_u64 v[212:213], s[30:31], 0, v[162:163]
	s_mov_b32 m0, s67
	ds_read_b128 v[172:175], v182 offset:16384
	ds_read_b128 v[176:179], v182 offset:17408
	ds_read_b128 v[184:187], v182 offset:18432
	ds_read_b128 v[188:191], v182 offset:19456
	ds_read_b128 v[192:195], v182 offset:20480
	ds_read_b128 v[196:199], v182 offset:21504
	ds_read_b128 v[202:205], v182 offset:22528
	ds_read_b128 v[206:209], v182 offset:23552
	global_load_lds_dwordx4 v[212:213], off
	s_add_i32 m0, s67, 0x2000
	s_add_u32 s68, s30, 0x80000
	v_lshl_add_u64 v[214:215], s[30:31], 0, v[166:167]
	s_addc_u32 s69, s31, 0
	s_add_i32 s67, s70, s41
	global_load_lds_dwordx4 v[214:215], off
	v_lshl_add_u64 v[216:217], s[68:69], 0, v[162:163]
	s_mov_b32 m0, s67
	v_lshl_add_u64 v[218:219], s[34:35], 0, v[164:165]
	global_load_lds_dwordx4 v[216:217], off
	v_lshl_add_u64 v[216:217], s[68:69], 0, v[166:167]
	s_add_i32 m0, s67, 0x2000
	s_nop 0
	global_load_lds_dwordx4 v[216:217], off
	v_lshl_add_u64 v[216:217], s[34:35], 0, v[160:161]
	s_mov_b32 m0, s27
	s_nop 0
	global_load_lds_dwordx4 v[216:217], off
	s_mov_b32 m0, s48
	s_nop 0
	global_load_lds_dwordx4 v[218:219], off
	s_waitcnt vmcnt(8)
	s_waitcnt lgkmcnt(0)
	s_setprio 1
	s_barrier
	v_mfma_f32_16x16x32_bf16 v[60:63], v[64:67], v[172:175], v[60:63]
	v_mfma_f32_16x16x32_bf16 v[56:59], v[80:83], v[172:175], v[56:59]
	v_mfma_f32_16x16x32_bf16 v[44:47], v[64:67], v[184:187], v[44:47]
	v_mfma_f32_16x16x32_bf16 v[40:43], v[80:83], v[184:187], v[40:43]
	v_mfma_f32_16x16x32_bf16 v[28:31], v[64:67], v[192:195], v[28:31]
	v_mfma_f32_16x16x32_bf16 v[24:27], v[80:83], v[192:195], v[24:27]
	v_mfma_f32_16x16x32_bf16 v[12:15], v[64:67], v[202:205], v[12:15]
	v_mfma_f32_16x16x32_bf16 v[8:11], v[80:83], v[202:205], v[8:11]
	v_mfma_f32_16x16x32_bf16 v[60:63], v[72:75], v[176:179], v[60:63]
	v_mfma_f32_16x16x32_bf16 v[56:59], v[84:87], v[176:179], v[56:59]
	v_mfma_f32_16x16x32_bf16 v[44:47], v[72:75], v[188:191], v[44:47]
	v_mfma_f32_16x16x32_bf16 v[40:43], v[84:87], v[188:191], v[40:43]
	v_mfma_f32_16x16x32_bf16 v[28:31], v[72:75], v[196:199], v[28:31]
	v_mfma_f32_16x16x32_bf16 v[24:27], v[84:87], v[196:199], v[24:27]
	v_mfma_f32_16x16x32_bf16 v[12:15], v[72:75], v[206:209], v[12:15]
	v_mfma_f32_16x16x32_bf16 v[8:11], v[84:87], v[206:209], v[8:11]
	s_setprio 0
	s_setprio 1
	v_mfma_f32_16x16x32_bf16 v[52:55], v[144:147], v[172:175], v[52:55]
	v_mfma_f32_16x16x32_bf16 v[48:51], v[152:155], v[172:175], v[48:51]
	v_mfma_f32_16x16x32_bf16 v[36:39], v[144:147], v[184:187], v[36:39]
	v_mfma_f32_16x16x32_bf16 v[32:35], v[152:155], v[184:187], v[32:35]
	v_mfma_f32_16x16x32_bf16 v[20:23], v[144:147], v[192:195], v[20:23]
	v_mfma_f32_16x16x32_bf16 v[16:19], v[152:155], v[192:195], v[16:19]
	v_mfma_f32_16x16x32_bf16 v[4:7], v[144:147], v[202:205], v[4:7]
	v_mfma_f32_16x16x32_bf16 v[0:3], v[152:155], v[202:205], v[0:3]
	v_mfma_f32_16x16x32_bf16 v[52:55], v[148:151], v[176:179], v[52:55]
	v_mfma_f32_16x16x32_bf16 v[48:51], v[156:159], v[176:179], v[48:51]
	v_mfma_f32_16x16x32_bf16 v[36:39], v[148:151], v[188:191], v[36:39]
	v_mfma_f32_16x16x32_bf16 v[32:35], v[156:159], v[188:191], v[32:35]
	v_mfma_f32_16x16x32_bf16 v[20:23], v[148:151], v[196:199], v[20:23]
	v_mfma_f32_16x16x32_bf16 v[16:19], v[156:159], v[196:199], v[16:19]
	v_mfma_f32_16x16x32_bf16 v[4:7], v[148:151], v[206:209], v[4:7]
	v_mfma_f32_16x16x32_bf16 v[0:3], v[156:159], v[206:209], v[0:3]
	s_barrier
	s_setprio 0
	s_add_i32 s67, 0, 0x18000
	s_add_i32 s68, 0, 0x1c000
	v_add_u32_e32 v84, s67, v181
	v_add_u32_e32 v156, s68, v181
	ds_read_b128 v[64:67], v84
	ds_read_b128 v[72:75], v84 offset:1024
	ds_read_b128 v[80:83], v84 offset:2048
	ds_read_b128 v[84:87], v84 offset:3072
	ds_read_b128 v[144:147], v156
	ds_read_b128 v[148:151], v156 offset:1024
	ds_read_b128 v[152:155], v156 offset:2048
	ds_read_b128 v[156:159], v156 offset:3072
	s_add_u32 s34, s34, 0x80000
	s_addc_u32 s35, s35, 0
	s_mov_b32 m0, s49
	v_lshl_add_u64 v[220:221], s[34:35], 0, v[160:161]
	ds_read_b128 v[172:175], v182 offset:32768
	ds_read_b128 v[176:179], v182 offset:33792
	ds_read_b128 v[184:187], v182 offset:34816
	ds_read_b128 v[188:191], v182 offset:35840
	ds_read_b128 v[192:195], v182 offset:36864
	ds_read_b128 v[196:199], v182 offset:37888
	ds_read_b128 v[202:205], v182 offset:38912
	ds_read_b128 v[206:209], v182 offset:39936
	global_load_lds_dwordx4 v[220:221], off
	v_lshl_add_u64 v[220:221], s[34:35], 0, v[164:165]
	s_mov_b32 m0, s50
	s_nop 0
	global_load_lds_dwordx4 v[220:221], off
	s_waitcnt vmcnt(8)
	s_waitcnt lgkmcnt(0)
	s_setprio 1
	s_barrier
	v_mfma_f32_16x16x32_bf16 v[140:143], v[64:67], v[172:175], v[140:143]
	v_mfma_f32_16x16x32_bf16 v[136:139], v[80:83], v[172:175], v[136:139]
	v_mfma_f32_16x16x32_bf16 v[124:127], v[64:67], v[184:187], v[124:127]
	v_mfma_f32_16x16x32_bf16 v[120:123], v[80:83], v[184:187], v[120:123]
	v_mfma_f32_16x16x32_bf16 v[108:111], v[64:67], v[192:195], v[108:111]
	v_mfma_f32_16x16x32_bf16 v[104:107], v[80:83], v[192:195], v[104:107]
	v_mfma_f32_16x16x32_bf16 v[92:95], v[64:67], v[202:205], v[92:95]
	v_mfma_f32_16x16x32_bf16 v[88:91], v[80:83], v[202:205], v[88:91]
	v_mfma_f32_16x16x32_bf16 v[140:143], v[72:75], v[176:179], v[140:143]
	v_mfma_f32_16x16x32_bf16 v[136:139], v[84:87], v[176:179], v[136:139]
	v_mfma_f32_16x16x32_bf16 v[124:127], v[72:75], v[188:191], v[124:127]
	v_mfma_f32_16x16x32_bf16 v[120:123], v[84:87], v[188:191], v[120:123]
	v_mfma_f32_16x16x32_bf16 v[108:111], v[72:75], v[196:199], v[108:111]
	v_mfma_f32_16x16x32_bf16 v[104:107], v[84:87], v[196:199], v[104:107]
	v_mfma_f32_16x16x32_bf16 v[92:95], v[72:75], v[206:209], v[92:95]
	v_mfma_f32_16x16x32_bf16 v[88:91], v[84:87], v[206:209], v[88:91]
	s_setprio 0
	s_setprio 1
	v_mfma_f32_16x16x32_bf16 v[132:135], v[144:147], v[172:175], v[132:135]
	v_mfma_f32_16x16x32_bf16 v[128:131], v[152:155], v[172:175], v[128:131]
	v_mfma_f32_16x16x32_bf16 v[116:119], v[144:147], v[184:187], v[116:119]
	v_mfma_f32_16x16x32_bf16 v[112:115], v[152:155], v[184:187], v[112:115]
	v_mfma_f32_16x16x32_bf16 v[100:103], v[144:147], v[192:195], v[100:103]
	v_mfma_f32_16x16x32_bf16 v[96:99], v[152:155], v[192:195], v[96:99]
	v_mfma_f32_16x16x32_bf16 v[76:79], v[144:147], v[202:205], v[76:79]
	v_mfma_f32_16x16x32_bf16 v[68:71], v[152:155], v[202:205], v[68:71]
	v_mfma_f32_16x16x32_bf16 v[132:135], v[148:151], v[176:179], v[132:135]
	v_mfma_f32_16x16x32_bf16 v[128:131], v[156:159], v[176:179], v[128:131]
	v_mfma_f32_16x16x32_bf16 v[116:119], v[148:151], v[188:191], v[116:119]
	v_mfma_f32_16x16x32_bf16 v[112:115], v[156:159], v[188:191], v[112:115]
	v_mfma_f32_16x16x32_bf16 v[100:103], v[148:151], v[196:199], v[100:103]
	v_mfma_f32_16x16x32_bf16 v[96:99], v[156:159], v[196:199], v[96:99]
	v_mfma_f32_16x16x32_bf16 v[76:79], v[148:151], v[206:209], v[76:79]
	v_mfma_f32_16x16x32_bf16 v[68:71], v[156:159], v[206:209], v[68:71]
	s_barrier
	s_setprio 0
	s_add_i32 s34, s67, s41
	v_lshl_add_u64 v[212:213], v[212:213], 0, s[64:65]
	s_mov_b32 m0, s34
	ds_read_b128 v[172:175], v182 offset:49152
	ds_read_b128 v[176:179], v182 offset:50176
	ds_read_b128 v[184:187], v182 offset:51200
	ds_read_b128 v[188:191], v182 offset:52224
	ds_read_b128 v[192:195], v182 offset:53248
	ds_read_b128 v[196:199], v182 offset:54272
	ds_read_b128 v[202:205], v182 offset:55296
	ds_read_b128 v[206:209], v182 offset:56320
	global_load_lds_dwordx4 v[212:213], off
	s_add_i32 m0, s34, 0x2000
	s_add_u32 s30, s30, 0x80080
	v_lshl_add_u64 v[212:213], v[214:215], 0, s[64:65]
	s_addc_u32 s31, s31, 0
	s_add_i32 s34, s68, s41
	global_load_lds_dwordx4 v[212:213], off
	v_lshl_add_u64 v[212:213], s[30:31], 0, v[162:163]
	s_mov_b32 m0, s34
	s_nop 0
	global_load_lds_dwordx4 v[212:213], off
	v_lshl_add_u64 v[212:213], s[30:31], 0, v[166:167]
	s_add_i32 m0, s34, 0x2000
	s_nop 0
	global_load_lds_dwordx4 v[212:213], off
	v_lshl_add_u64 v[212:213], v[216:217], 0, s[64:65]
	s_mov_b32 m0, s53
	s_nop 0
	global_load_lds_dwordx4 v[212:213], off
	v_lshl_add_u64 v[212:213], v[218:219], 0, s[64:65]
	s_mov_b32 m0, s56
	s_nop 0
	global_load_lds_dwordx4 v[212:213], off
	s_waitcnt vmcnt(8)
	s_waitcnt lgkmcnt(0)
	s_setprio 1
	s_barrier
	v_mfma_f32_16x16x32_bf16 v[60:63], v[64:67], v[172:175], v[60:63]
	v_mfma_f32_16x16x32_bf16 v[56:59], v[80:83], v[172:175], v[56:59]
	v_mfma_f32_16x16x32_bf16 v[44:47], v[64:67], v[184:187], v[44:47]
	v_mfma_f32_16x16x32_bf16 v[40:43], v[80:83], v[184:187], v[40:43]
	v_mfma_f32_16x16x32_bf16 v[28:31], v[64:67], v[192:195], v[28:31]
	v_mfma_f32_16x16x32_bf16 v[24:27], v[80:83], v[192:195], v[24:27]
	v_mfma_f32_16x16x32_bf16 v[12:15], v[64:67], v[202:205], v[12:15]
	v_mfma_f32_16x16x32_bf16 v[8:11], v[80:83], v[202:205], v[8:11]
	v_mfma_f32_16x16x32_bf16 v[60:63], v[72:75], v[176:179], v[60:63]
	v_mfma_f32_16x16x32_bf16 v[56:59], v[84:87], v[176:179], v[56:59]
	v_mfma_f32_16x16x32_bf16 v[44:47], v[72:75], v[188:191], v[44:47]
	v_mfma_f32_16x16x32_bf16 v[40:43], v[84:87], v[188:191], v[40:43]
	v_mfma_f32_16x16x32_bf16 v[28:31], v[72:75], v[196:199], v[28:31]
	v_mfma_f32_16x16x32_bf16 v[24:27], v[84:87], v[196:199], v[24:27]
	v_mfma_f32_16x16x32_bf16 v[12:15], v[72:75], v[206:209], v[12:15]
	v_mfma_f32_16x16x32_bf16 v[8:11], v[84:87], v[206:209], v[8:11]
	s_setprio 0
	s_setprio 1
	v_mfma_f32_16x16x32_bf16 v[52:55], v[144:147], v[172:175], v[52:55]
	v_mfma_f32_16x16x32_bf16 v[48:51], v[152:155], v[172:175], v[48:51]
	v_mfma_f32_16x16x32_bf16 v[36:39], v[144:147], v[184:187], v[36:39]
	v_mfma_f32_16x16x32_bf16 v[32:35], v[152:155], v[184:187], v[32:35]
	v_mfma_f32_16x16x32_bf16 v[20:23], v[144:147], v[192:195], v[20:23]
	v_mfma_f32_16x16x32_bf16 v[16:19], v[152:155], v[192:195], v[16:19]
	v_mfma_f32_16x16x32_bf16 v[4:7], v[144:147], v[202:205], v[4:7]
	v_mfma_f32_16x16x32_bf16 v[0:3], v[152:155], v[202:205], v[0:3]
	v_mfma_f32_16x16x32_bf16 v[52:55], v[148:151], v[176:179], v[52:55]
	v_mfma_f32_16x16x32_bf16 v[48:51], v[156:159], v[176:179], v[48:51]
	v_mfma_f32_16x16x32_bf16 v[36:39], v[148:151], v[188:191], v[36:39]
	v_mfma_f32_16x16x32_bf16 v[32:35], v[156:159], v[188:191], v[32:35]
	v_mfma_f32_16x16x32_bf16 v[20:23], v[148:151], v[196:199], v[20:23]
	v_mfma_f32_16x16x32_bf16 v[16:19], v[156:159], v[196:199], v[16:19]
	v_mfma_f32_16x16x32_bf16 v[4:7], v[148:151], v[206:209], v[4:7]
	v_mfma_f32_16x16x32_bf16 v[0:3], v[156:159], v[206:209], v[0:3]
	s_barrier
	s_setprio 0
	s_add_i32 s66, s66, 2
	s_add_u32 s28, s28, 0x100
	s_addc_u32 s29, s29, 0
	s_add_u32 s62, s62, 0x100
	s_addc_u32 s63, s63, 0
	s_cmp_gt_u32 s66, 29
	s_cbranch_scc0 .LBB0_189
	s_and_b64 vcc, exec, s[16:17]
	s_cbranch_vccz .LBB0_192
	s_barrier

.LBB0_209:
.LBB0_210:
	s_lshl_b32 s19, s26, 8
	s_mul_hi_i32 s7, s19, 0x2aaaaaab
	s_lshr_b32 s21, s7, 31
	s_lshr_b32 s7, s7, 9
	s_add_i32 s7, s7, s21
	s_mulk_i32 s7, 0xc00
	s_sub_i32 s21, s19, s7
	s_cmpk_lt_i32 s21, 0x800
	v_mbcnt_lo_u32_b32 v173, -1, 0
	v_mbcnt_hi_u32_b32 v173, -1, v173
	s_cselect_b64 s[28:29], -1, 0
	v_bfe_u32 v172, v173, 4, 2
	s_lshl_b32 s6, s6, 8
	v_lshlrev_b32_e32 v175, 3, v172
	s_and_b64 s[28:29], s[28:29], s[76:77]
	s_add_i32 s6, s6, s78
	v_and_b32_e32 v64, 8, v175
	v_cndmask_b32_e64 v65, 0, 1, s[28:29]
	v_and_or_b32 v184, v173, 15, s6
	v_mov_b32_e32 v152, 0
	v_cmp_ne_u32_e64 s[6:7], 1, v65
	s_andn2_b64 vcc, exec, s[28:29]
	v_lshlrev_b32_e32 v176, 2, v64
	v_mov_b32_e32 v153, 0
	v_mov_b32_e32 v154, 0
	v_mov_b32_e32 v155, 0
	v_mov_b32_e32 v144, 0
	v_mov_b32_e32 v145, 0
	v_mov_b32_e32 v146, 0
	v_mov_b32_e32 v147, 0
	v_mov_b32_e32 v84, 0
	v_mov_b32_e32 v85, 0
	v_mov_b32_e32 v86, 0
	v_mov_b32_e32 v87, 0
	v_mov_b32_e32 v72, 0
	v_mov_b32_e32 v73, 0
	v_mov_b32_e32 v74, 0
	v_mov_b32_e32 v75, 0
	v_mov_b32_e32 v156, 0
	v_mov_b32_e32 v157, 0
	v_mov_b32_e32 v158, 0
	v_mov_b32_e32 v159, 0
	v_mov_b32_e32 v148, 0
	v_mov_b32_e32 v149, 0
	v_mov_b32_e32 v150, 0
	v_mov_b32_e32 v151, 0
	v_mov_b32_e32 v80, 0
	v_mov_b32_e32 v81, 0
	v_mov_b32_e32 v82, 0
	v_mov_b32_e32 v83, 0
	v_mov_b32_e32 v64, 0
	v_mov_b32_e32 v65, 0
	v_mov_b32_e32 v66, 0
	v_mov_b32_e32 v67, 0
	s_cbranch_vccnz .LBB0_212
	v_mov_b32_e32 v177, v201
	v_and_b32_e32 v246, s51, v184
	v_lshl_add_u32 v246, v246, 7, v176
	global_load_dwordx4 v[148:151], v246, s[14:15] offset:16
	global_load_dwordx4 v[156:159], v246, s[14:15]
	global_load_dwordx4 v[144:147], v246, s[14:15] offset:80
	global_load_dwordx4 v[152:155], v246, s[14:15] offset:64
	v_add_u32_e32 v247, 16, v184
	v_and_b32_e32 v247, s51, v247
	v_lshl_add_u32 v247, v247, 7, v176
	global_load_dwordx4 v[64:67], v247, s[14:15] offset:16
	global_load_dwordx4 v[80:83], v247, s[14:15]
	global_load_dwordx4 v[72:75], v247, s[14:15] offset:80
	global_load_dwordx4 v[84:87], v247, s[14:15] offset:64
	s_waitcnt vmcnt(4)

.LBB0_216:
	v_mov_b32_e32 v175, v174
	v_mov_b32_e32 v138, v174
	v_mov_b32_e32 v139, v174
	v_pk_mul_f32 v[134:135], v[138:139], v[134:135]
	v_pk_mul_f32 v[138:139], v[138:139], v[130:131]
	v_pk_mul_f32 v[130:131], v[174:175], v[128:129]
	v_pk_mul_f32 v[132:133], v[174:175], v[132:133]
	s_and_b64 vcc, exec, s[6:7]
	v_cvt_pk_bf16_f32 v128, v132, v133
	v_cvt_pk_bf16_f32 v129, v134, v135
	v_cvt_pk_bf16_f32 v130, v130, v131
	v_cvt_pk_bf16_f32 v131, v138, v139
	global_store_dwordx4 v[136:137], v[128:131], off offset:256 nt
	s_nop 1
	v_or_b32_e32 v130, 16, v184
	s_cbranch_vccnz .LBB0_218
	v_add_u32_e32 v246, 32, v184
	v_and_b32_e32 v246, s51, v246
	v_lshl_add_u32 v246, v246, 7, v176
	global_load_dwordx4 v[148:151], v246, s[14:15] offset:16
	global_load_dwordx4 v[156:159], v246, s[14:15]
	global_load_dwordx4 v[144:147], v246, s[14:15] offset:80
	global_load_dwordx4 v[152:155], v246, s[14:15] offset:64
.LBB0_218:
	s_and_b64 vcc, exec, s[6:7]
	s_cbranch_vccnz .LBB0_220
	ds_bpermute_b32 v128, v183, v124
	ds_bpermute_b32 v129, v183, v125
	ds_bpermute_b32 v132, v183, v126
	ds_bpermute_b32 v133, v183, v127
	v_mov_b32_e32 v134, v172
	v_mov_b32_e32 v135, v172
	s_waitcnt vmcnt(6) lgkmcnt(0)
	v_pk_mul_f32 v[128:129], v[84:85], v[128:129]
	v_pk_mul_f32 v[132:133], v[86:87], v[132:133]
	v_pk_mul_f32 v[128:129], v[172:173], v[128:129]
	v_pk_mul_f32 v[132:133], v[134:135], v[132:133]
	v_pk_fma_f32 v[124:125], v[124:125], v[80:81], v[128:129]
	v_pk_fma_f32 v[126:127], v[126:127], v[82:83], v[132:133]
	ds_bpermute_b32 v128, v183, v120
	ds_bpermute_b32 v129, v183, v121
	ds_bpermute_b32 v132, v183, v122
	ds_bpermute_b32 v133, v183, v123
	s_waitcnt lgkmcnt(2)
	v_pk_mul_f32 v[128:129], v[72:73], v[128:129]
	s_nop 0
	v_pk_mul_f32 v[128:129], v[172:173], v[128:129]
	s_waitcnt lgkmcnt(0)
	v_pk_mul_f32 v[132:133], v[74:75], v[132:133]
	v_pk_fma_f32 v[120:121], v[120:121], v[64:65], v[128:129]
	v_pk_mul_f32 v[132:133], v[134:135], v[132:133]
	s_nop 0
	v_pk_fma_f32 v[122:123], v[122:123], v[66:67], v[132:133]
.LBB0_220:
	v_mov_b32_e32 v128, v174
	v_mov_b32_e32 v129, v174
	v_pk_mul_f32 v[124:125], v[174:175], v[124:125]
	v_pk_mul_f32 v[120:121], v[174:175], v[120:121]
	v_pk_mul_f32 v[126:127], v[128:129], v[126:127]
	v_pk_mul_f32 v[132:133], v[128:129], v[122:123]
	v_cvt_pk_bf16_f32 v122, v124, v125
	v_cvt_pk_bf16_f32 v123, v126, v127
	v_cvt_pk_bf16_f32 v124, v120, v121
	v_mov_b64_e32 v[120:121], s[12:13]
	v_mad_i64_i32 v[120:121], s[28:29], v130, s88, v[120:121]
	v_lshl_add_u64 v[120:121], v[178:179], 1, v[120:121]
	s_and_b64 vcc, exec, s[6:7]
	v_cvt_pk_bf16_f32 v125, v132, v133
	global_store_dwordx4 v[120:121], v[122:125], off nt
	s_cbranch_vccnz .LBB0_222
	ds_bpermute_b32 v122, v183, v116
	ds_bpermute_b32 v123, v183, v117
	ds_bpermute_b32 v124, v183, v118
	ds_bpermute_b32 v125, v183, v119
	v_mov_b32_e32 v126, v172
	v_mov_b32_e32 v127, v172
	s_waitcnt lgkmcnt(0)
	v_pk_mul_f32 v[122:123], v[84:85], v[122:123]
	v_pk_mul_f32 v[124:125], v[86:87], v[124:125]
	v_pk_mul_f32 v[122:123], v[172:173], v[122:123]
	v_pk_mul_f32 v[124:125], v[126:127], v[124:125]
	v_pk_fma_f32 v[116:117], v[116:117], v[80:81], v[122:123]
	v_pk_fma_f32 v[118:119], v[118:119], v[82:83], v[124:125]
	ds_bpermute_b32 v122, v183, v112
	ds_bpermute_b32 v123, v183, v113
	ds_bpermute_b32 v124, v183, v114
	ds_bpermute_b32 v125, v183, v115
	s_waitcnt lgkmcnt(2)
	v_pk_mul_f32 v[122:123], v[72:73], v[122:123]
	s_nop 0
	v_pk_mul_f32 v[122:123], v[172:173], v[122:123]
	s_waitcnt lgkmcnt(0)
	v_pk_mul_f32 v[124:125], v[74:75], v[124:125]
	v_pk_fma_f32 v[112:113], v[112:113], v[64:65], v[122:123]
	v_pk_mul_f32 v[124:125], v[126:127], v[124:125]
	s_nop 0
	v_pk_fma_f32 v[114:115], v[114:115], v[66:67], v[124:125]
.LBB0_222:
	s_nop 0
	v_pk_mul_f32 v[122:123], v[128:129], v[114:115]
	v_pk_mul_f32 v[114:115], v[174:175], v[112:113]
	v_pk_mul_f32 v[118:119], v[128:129], v[118:119]
	v_pk_mul_f32 v[116:117], v[174:175], v[116:117]
	s_and_b64 vcc, exec, s[6:7]
	v_cvt_pk_bf16_f32 v112, v116, v117
	v_cvt_pk_bf16_f32 v113, v118, v119
	v_cvt_pk_bf16_f32 v114, v114, v115
	v_cvt_pk_bf16_f32 v115, v122, v123
	global_store_dwordx4 v[120:121], v[112:115], off offset:256 nt
	s_nop 1
	v_or_b32_e32 v114, 32, v184
	s_cbranch_vccnz .LBB0_224
	v_add_u32_e32 v246, 48, v184
	v_and_b32_e32 v246, s51, v246
	v_lshl_add_u32 v246, v246, 7, v176
	global_load_dwordx4 v[64:67], v246, s[14:15] offset:16
	global_load_dwordx4 v[80:83], v246, s[14:15]
	global_load_dwordx4 v[72:75], v246, s[14:15] offset:80
	global_load_dwordx4 v[84:87], v246, s[14:15] offset:64
.LBB0_224:
	s_and_b64 vcc, exec, s[6:7]
	s_cbranch_vccnz .LBB0_226
	ds_bpermute_b32 v112, v183, v108
	ds_bpermute_b32 v113, v183, v109
	ds_bpermute_b32 v116, v183, v110
	ds_bpermute_b32 v117, v183, v111
	v_mov_b32_e32 v118, v172
	v_mov_b32_e32 v119, v172
	s_waitcnt vmcnt(6) lgkmcnt(0)
	v_pk_mul_f32 v[112:113], v[152:153], v[112:113]
	v_pk_mul_f32 v[116:117], v[154:155], v[116:117]
	v_pk_mul_f32 v[112:113], v[172:173], v[112:113]
	v_pk_mul_f32 v[116:117], v[118:119], v[116:117]
	v_pk_fma_f32 v[108:109], v[108:109], v[156:157], v[112:113]
	v_pk_fma_f32 v[110:111], v[110:111], v[158:159], v[116:117]
	ds_bpermute_b32 v112, v183, v104
	ds_bpermute_b32 v113, v183, v105
	ds_bpermute_b32 v116, v183, v106
	ds_bpermute_b32 v117, v183, v107
	s_waitcnt lgkmcnt(2)
	v_pk_mul_f32 v[112:113], v[144:145], v[112:113]
	s_nop 0
	v_pk_mul_f32 v[112:113], v[172:173], v[112:113]
	s_waitcnt lgkmcnt(0)
	v_pk_mul_f32 v[116:117], v[146:147], v[116:117]
	v_pk_fma_f32 v[104:105], v[104:105], v[148:149], v[112:113]
	v_pk_mul_f32 v[116:117], v[118:119], v[116:117]
	s_nop 0
	v_pk_fma_f32 v[106:107], v[106:107], v[150:151], v[116:117]
.LBB0_226:
	v_mov_b32_e32 v112, v174
	v_mov_b32_e32 v113, v174
	v_pk_mul_f32 v[108:109], v[174:175], v[108:109]
	v_pk_mul_f32 v[104:105], v[174:175], v[104:105]
	v_pk_mul_f32 v[110:111], v[112:113], v[110:111]
	v_pk_mul_f32 v[116:117], v[112:113], v[106:107]
	v_cvt_pk_bf16_f32 v106, v108, v109
	v_cvt_pk_bf16_f32 v107, v110, v111
	v_cvt_pk_bf16_f32 v108, v104, v105
	v_mov_b64_e32 v[104:105], s[12:13]
	v_mad_i64_i32 v[104:105], s[28:29], v114, s88, v[104:105]
	v_lshl_add_u64 v[104:105], v[178:179], 1, v[104:105]
	s_and_b64 vcc, exec, s[6:7]
	v_cvt_pk_bf16_f32 v109, v116, v117
	global_store_dwordx4 v[104:105], v[106:109], off nt
	s_cbranch_vccnz .LBB0_228
	ds_bpermute_b32 v106, v183, v100
	ds_bpermute_b32 v107, v183, v101
	ds_bpermute_b32 v108, v183, v102
	ds_bpermute_b32 v109, v183, v103
	v_mov_b32_e32 v110, v172
	v_mov_b32_e32 v111, v172
	s_waitcnt lgkmcnt(0)
	v_pk_mul_f32 v[106:107], v[152:153], v[106:107]
	v_pk_mul_f32 v[108:109], v[154:155], v[108:109]
	v_pk_mul_f32 v[106:107], v[172:173], v[106:107]
	v_pk_mul_f32 v[108:109], v[110:111], v[108:109]
	v_pk_fma_f32 v[100:101], v[100:101], v[156:157], v[106:107]
	v_pk_fma_f32 v[102:103], v[102:103], v[158:159], v[108:109]
	ds_bpermute_b32 v106, v183, v96
	ds_bpermute_b32 v107, v183, v97
	ds_bpermute_b32 v108, v183, v98
	ds_bpermute_b32 v109, v183, v99
	s_waitcnt lgkmcnt(2)
	v_pk_mul_f32 v[106:107], v[144:145], v[106:107]
	s_nop 0
	v_pk_mul_f32 v[106:107], v[172:173], v[106:107]
	s_waitcnt lgkmcnt(0)
	v_pk_mul_f32 v[108:109], v[146:147], v[108:109]
	v_pk_fma_f32 v[96:97], v[96:97], v[148:149], v[106:107]
	v_pk_mul_f32 v[108:109], v[110:111], v[108:109]
	s_nop 0
	v_pk_fma_f32 v[98:99], v[98:99], v[150:151], v[108:109]
.LBB0_228:
	s_nop 0
	v_pk_mul_f32 v[106:107], v[112:113], v[98:99]
	v_pk_mul_f32 v[98:99], v[174:175], v[96:97]
	v_pk_mul_f32 v[102:103], v[112:113], v[102:103]
	v_pk_mul_f32 v[100:101], v[174:175], v[100:101]
	s_and_b64 vcc, exec, s[6:7]
	v_cvt_pk_bf16_f32 v96, v100, v101
	v_cvt_pk_bf16_f32 v97, v102, v103
	v_cvt_pk_bf16_f32 v98, v98, v99
	v_cvt_pk_bf16_f32 v99, v106, v107
	global_store_dwordx4 v[104:105], v[96:99], off offset:256 nt
	s_nop 1
	v_or_b32_e32 v98, 48, v184
	s_cbranch_vccnz .LBB0_230
	v_add_u32_e32 v246, 0x80, v184
	v_and_b32_e32 v246, s51, v246
	v_lshl_add_u32 v246, v246, 7, v176
	global_load_dwordx4 v[148:151], v246, s[14:15] offset:16
	global_load_dwordx4 v[156:159], v246, s[14:15]
	global_load_dwordx4 v[144:147], v246, s[14:15] offset:80
	global_load_dwordx4 v[152:155], v246, s[14:15] offset:64
.LBB0_230:
	s_and_b64 vcc, exec, s[6:7]
	s_cbranch_vccnz .LBB0_232
	ds_bpermute_b32 v96, v183, v92
	ds_bpermute_b32 v97, v183, v93
	ds_bpermute_b32 v100, v183, v94
	ds_bpermute_b32 v101, v183, v95
	v_mov_b32_e32 v102, v172
	v_mov_b32_e32 v103, v172
	s_waitcnt vmcnt(6) lgkmcnt(0)
	v_pk_mul_f32 v[96:97], v[84:85], v[96:97]
	v_pk_mul_f32 v[100:101], v[86:87], v[100:101]
	v_pk_mul_f32 v[96:97], v[172:173], v[96:97]
	v_pk_mul_f32 v[100:101], v[102:103], v[100:101]
	v_pk_fma_f32 v[92:93], v[92:93], v[80:81], v[96:97]
	v_pk_fma_f32 v[94:95], v[94:95], v[82:83], v[100:101]
	ds_bpermute_b32 v96, v183, v88
	ds_bpermute_b32 v97, v183, v89
	ds_bpermute_b32 v100, v183, v90
	ds_bpermute_b32 v101, v183, v91
	s_waitcnt lgkmcnt(2)
	v_pk_mul_f32 v[96:97], v[72:73], v[96:97]
	s_nop 0
	v_pk_mul_f32 v[96:97], v[172:173], v[96:97]
	s_waitcnt lgkmcnt(0)
	v_pk_mul_f32 v[100:101], v[74:75], v[100:101]
	v_pk_fma_f32 v[88:89], v[88:89], v[64:65], v[96:97]
	v_pk_mul_f32 v[100:101], v[102:103], v[100:101]
	s_nop 0
	v_pk_fma_f32 v[90:91], v[90:91], v[66:67], v[100:101]
.LBB0_232:
	v_mov_b32_e32 v96, v174
	v_mov_b32_e32 v97, v174
	v_pk_mul_f32 v[92:93], v[174:175], v[92:93]
	v_pk_mul_f32 v[88:89], v[174:175], v[88:89]
	v_pk_mul_f32 v[94:95], v[96:97], v[94:95]
	v_pk_mul_f32 v[100:101], v[96:97], v[90:91]
	v_cvt_pk_bf16_f32 v90, v92, v93
	v_cvt_pk_bf16_f32 v91, v94, v95
	v_cvt_pk_bf16_f32 v92, v88, v89
	v_mov_b64_e32 v[88:89], s[12:13]
	v_mad_i64_i32 v[88:89], s[28:29], v98, s88, v[88:89]
	v_lshl_add_u64 v[88:89], v[178:179], 1, v[88:89]
	s_and_b64 vcc, exec, s[6:7]
	v_cvt_pk_bf16_f32 v93, v100, v101
	global_store_dwordx4 v[88:89], v[90:93], off nt
	s_cbranch_vccnz .LBB0_234
	ds_bpermute_b32 v90, v183, v76
	ds_bpermute_b32 v91, v183, v77
	ds_bpermute_b32 v92, v183, v78
	ds_bpermute_b32 v93, v183, v79
	v_mov_b32_e32 v94, v172
	v_mov_b32_e32 v95, v172
	s_waitcnt lgkmcnt(0)
	v_pk_mul_f32 v[90:91], v[84:85], v[90:91]
	v_pk_mul_f32 v[92:93], v[86:87], v[92:93]
	v_pk_mul_f32 v[90:91], v[172:173], v[90:91]
	v_pk_mul_f32 v[92:93], v[94:95], v[92:93]
	v_pk_fma_f32 v[76:77], v[76:77], v[80:81], v[90:91]
	v_pk_fma_f32 v[78:79], v[78:79], v[82:83], v[92:93]
	ds_bpermute_b32 v90, v183, v68
	ds_bpermute_b32 v91, v183, v69
	ds_bpermute_b32 v92, v183, v70
	ds_bpermute_b32 v93, v183, v71
	s_waitcnt lgkmcnt(2)
	v_pk_mul_f32 v[90:91], v[72:73], v[90:91]
	s_nop 0
	v_pk_mul_f32 v[90:91], v[172:173], v[90:91]
	s_waitcnt lgkmcnt(0)
	v_pk_mul_f32 v[92:93], v[74:75], v[92:93]
	v_pk_fma_f32 v[68:69], v[68:69], v[64:65], v[90:91]
	v_pk_mul_f32 v[92:93], v[94:95], v[92:93]
	s_nop 0
	v_pk_fma_f32 v[70:71], v[70:71], v[66:67], v[92:93]
.LBB0_234:
	s_nop 0
	v_pk_mul_f32 v[90:91], v[96:97], v[70:71]
	v_pk_mul_f32 v[70:71], v[174:175], v[68:69]
	v_pk_mul_f32 v[78:79], v[96:97], v[78:79]
	v_pk_mul_f32 v[76:77], v[174:175], v[76:77]
	s_and_b64 vcc, exec, s[6:7]
	v_cvt_pk_bf16_f32 v68, v76, v77
	v_cvt_pk_bf16_f32 v69, v78, v79
	v_cvt_pk_bf16_f32 v70, v70, v71
	v_cvt_pk_bf16_f32 v71, v90, v91
	global_store_dwordx4 v[88:89], v[68:71], off offset:256 nt
	s_nop 1
	v_add_u32_e32 v70, 0x80, v184
	s_cbranch_vccnz .LBB0_236
	v_add_u32_e32 v246, 0x90, v184
	v_and_b32_e32 v246, s51, v246
	v_lshl_add_u32 v246, v246, 7, v176
	global_load_dwordx4 v[64:67], v246, s[14:15] offset:16
	global_load_dwordx4 v[80:83], v246, s[14:15]
	global_load_dwordx4 v[72:75], v246, s[14:15] offset:80
	global_load_dwordx4 v[84:87], v246, s[14:15] offset:64
.LBB0_236:
	s_and_b64 vcc, exec, s[6:7]
	s_cbranch_vccnz .LBB0_238
	ds_bpermute_b32 v68, v183, v60
	ds_bpermute_b32 v69, v183, v61
	ds_bpermute_b32 v76, v183, v62
	ds_bpermute_b32 v77, v183, v63
	v_mov_b32_e32 v78, v172
	v_mov_b32_e32 v79, v172
	s_waitcnt vmcnt(6) lgkmcnt(0)
	v_pk_mul_f32 v[68:69], v[152:153], v[68:69]
	v_pk_mul_f32 v[76:77], v[154:155], v[76:77]
	v_pk_mul_f32 v[68:69], v[172:173], v[68:69]
	v_pk_mul_f32 v[76:77], v[78:79], v[76:77]
	v_pk_fma_f32 v[60:61], v[60:61], v[156:157], v[68:69]
	v_pk_fma_f32 v[62:63], v[62:63], v[158:159], v[76:77]
	ds_bpermute_b32 v68, v183, v56
	ds_bpermute_b32 v69, v183, v57
	ds_bpermute_b32 v76, v183, v58
	ds_bpermute_b32 v77, v183, v59
	s_waitcnt lgkmcnt(2)
	v_pk_mul_f32 v[68:69], v[144:145], v[68:69]
	s_nop 0
	v_pk_mul_f32 v[68:69], v[172:173], v[68:69]
	s_waitcnt lgkmcnt(0)
	v_pk_mul_f32 v[76:77], v[146:147], v[76:77]
	v_pk_fma_f32 v[56:57], v[56:57], v[148:149], v[68:69]
	v_pk_mul_f32 v[76:77], v[78:79], v[76:77]
	s_nop 0
	v_pk_fma_f32 v[58:59], v[58:59], v[150:151], v[76:77]
.LBB0_238:
	v_mov_b32_e32 v68, v174
	v_mov_b32_e32 v69, v174
	v_pk_mul_f32 v[60:61], v[174:175], v[60:61]
	v_pk_mul_f32 v[56:57], v[174:175], v[56:57]
	v_pk_mul_f32 v[62:63], v[68:69], v[62:63]
	v_pk_mul_f32 v[76:77], v[68:69], v[58:59]
	v_cvt_pk_bf16_f32 v58, v60, v61
	v_cvt_pk_bf16_f32 v59, v62, v63
	v_cvt_pk_bf16_f32 v60, v56, v57
	v_mov_b64_e32 v[56:57], s[12:13]
	v_mad_i64_i32 v[56:57], s[28:29], v70, s88, v[56:57]
	v_lshl_add_u64 v[56:57], v[178:179], 1, v[56:57]
	s_and_b64 vcc, exec, s[6:7]
	v_cvt_pk_bf16_f32 v61, v76, v77
	global_store_dwordx4 v[56:57], v[58:61], off nt
	s_cbranch_vccnz .LBB0_240
	ds_bpermute_b32 v58, v183, v52
	ds_bpermute_b32 v59, v183, v53
	ds_bpermute_b32 v60, v183, v54
	ds_bpermute_b32 v61, v183, v55
	v_mov_b32_e32 v62, v172
	v_mov_b32_e32 v63, v172
	s_waitcnt lgkmcnt(0)
	v_pk_mul_f32 v[58:59], v[152:153], v[58:59]
	v_pk_mul_f32 v[60:61], v[154:155], v[60:61]
	v_pk_mul_f32 v[58:59], v[172:173], v[58:59]
	v_pk_mul_f32 v[60:61], v[62:63], v[60:61]
	v_pk_fma_f32 v[52:53], v[52:53], v[156:157], v[58:59]
	v_pk_fma_f32 v[54:55], v[54:55], v[158:159], v[60:61]
	ds_bpermute_b32 v58, v183, v48
	ds_bpermute_b32 v59, v183, v49
	ds_bpermute_b32 v60, v183, v50
	ds_bpermute_b32 v61, v183, v51
	s_waitcnt lgkmcnt(2)
	v_pk_mul_f32 v[58:59], v[144:145], v[58:59]
	s_nop 0
	v_pk_mul_f32 v[58:59], v[172:173], v[58:59]
	s_waitcnt lgkmcnt(0)
	v_pk_mul_f32 v[60:61], v[146:147], v[60:61]
	v_pk_fma_f32 v[48:49], v[48:49], v[148:149], v[58:59]
	v_pk_mul_f32 v[60:61], v[62:63], v[60:61]
	s_nop 0
	v_pk_fma_f32 v[50:51], v[50:51], v[150:151], v[60:61]
.LBB0_240:
	s_nop 0
	v_pk_mul_f32 v[58:59], v[68:69], v[50:51]
	v_pk_mul_f32 v[50:51], v[174:175], v[48:49]
	v_pk_mul_f32 v[54:55], v[68:69], v[54:55]
	v_pk_mul_f32 v[52:53], v[174:175], v[52:53]
	s_and_b64 vcc, exec, s[6:7]
	v_cvt_pk_bf16_f32 v48, v52, v53
	v_cvt_pk_bf16_f32 v49, v54, v55
	v_cvt_pk_bf16_f32 v50, v50, v51
	v_cvt_pk_bf16_f32 v51, v58, v59
	global_store_dwordx4 v[56:57], v[48:51], off offset:256 nt
	s_nop 1
	v_add_u32_e32 v50, 0x90, v184
	s_cbranch_vccnz .LBB0_242
	v_add_u32_e32 v246, 0xa0, v184
	v_and_b32_e32 v246, s51, v246
	v_lshl_add_u32 v246, v246, 7, v176
	global_load_dwordx4 v[148:151], v246, s[14:15] offset:16
	global_load_dwordx4 v[156:159], v246, s[14:15]
	global_load_dwordx4 v[144:147], v246, s[14:15] offset:80
	global_load_dwordx4 v[152:155], v246, s[14:15] offset:64
.LBB0_242:
	s_and_b64 vcc, exec, s[6:7]
	s_cbranch_vccnz .LBB0_244
	ds_bpermute_b32 v48, v183, v44
	ds_bpermute_b32 v49, v183, v45
	ds_bpermute_b32 v52, v183, v46
	ds_bpermute_b32 v53, v183, v47
	v_mov_b32_e32 v54, v172
	v_mov_b32_e32 v55, v172
	s_waitcnt vmcnt(6) lgkmcnt(0)
	v_pk_mul_f32 v[48:49], v[84:85], v[48:49]
	v_pk_mul_f32 v[52:53], v[86:87], v[52:53]
	v_pk_mul_f32 v[48:49], v[172:173], v[48:49]
	v_pk_mul_f32 v[52:53], v[54:55], v[52:53]
	v_pk_fma_f32 v[44:45], v[44:45], v[80:81], v[48:49]
	v_pk_fma_f32 v[46:47], v[46:47], v[82:83], v[52:53]
	ds_bpermute_b32 v48, v183, v40
	ds_bpermute_b32 v49, v183, v41
	ds_bpermute_b32 v52, v183, v42
	ds_bpermute_b32 v53, v183, v43
	s_waitcnt lgkmcnt(2)
	v_pk_mul_f32 v[48:49], v[72:73], v[48:49]
	s_nop 0
	v_pk_mul_f32 v[48:49], v[172:173], v[48:49]
	s_waitcnt lgkmcnt(0)
	v_pk_mul_f32 v[52:53], v[74:75], v[52:53]
	v_pk_fma_f32 v[40:41], v[40:41], v[64:65], v[48:49]
	v_pk_mul_f32 v[52:53], v[54:55], v[52:53]
	s_nop 0
	v_pk_fma_f32 v[42:43], v[42:43], v[66:67], v[52:53]
.LBB0_244:
	v_mov_b32_e32 v48, v174
	v_mov_b32_e32 v49, v174
	v_pk_mul_f32 v[44:45], v[174:175], v[44:45]
	v_pk_mul_f32 v[40:41], v[174:175], v[40:41]
	v_pk_mul_f32 v[46:47], v[48:49], v[46:47]
	v_pk_mul_f32 v[52:53], v[48:49], v[42:43]
	v_cvt_pk_bf16_f32 v42, v44, v45
	v_cvt_pk_bf16_f32 v43, v46, v47
	v_cvt_pk_bf16_f32 v44, v40, v41
	v_mov_b64_e32 v[40:41], s[12:13]
	v_mad_i64_i32 v[40:41], s[28:29], v50, s88, v[40:41]
	v_lshl_add_u64 v[40:41], v[178:179], 1, v[40:41]
	s_and_b64 vcc, exec, s[6:7]
	v_cvt_pk_bf16_f32 v45, v52, v53
	global_store_dwordx4 v[40:41], v[42:45], off nt
	s_cbranch_vccnz .LBB0_246
	ds_bpermute_b32 v42, v183, v36
	ds_bpermute_b32 v43, v183, v37
	ds_bpermute_b32 v44, v183, v38
	ds_bpermute_b32 v45, v183, v39
	v_mov_b32_e32 v46, v172
	v_mov_b32_e32 v47, v172
	s_waitcnt lgkmcnt(0)
	v_pk_mul_f32 v[42:43], v[84:85], v[42:43]
	v_pk_mul_f32 v[44:45], v[86:87], v[44:45]
	v_pk_mul_f32 v[42:43], v[172:173], v[42:43]
	v_pk_mul_f32 v[44:45], v[46:47], v[44:45]
	v_pk_fma_f32 v[36:37], v[36:37], v[80:81], v[42:43]
	v_pk_fma_f32 v[38:39], v[38:39], v[82:83], v[44:45]
	ds_bpermute_b32 v42, v183, v32
	ds_bpermute_b32 v43, v183, v33
	ds_bpermute_b32 v44, v183, v34
	ds_bpermute_b32 v45, v183, v35
	s_waitcnt lgkmcnt(2)
	v_pk_mul_f32 v[42:43], v[72:73], v[42:43]
	s_nop 0
	v_pk_mul_f32 v[42:43], v[172:173], v[42:43]
	s_waitcnt lgkmcnt(0)
	v_pk_mul_f32 v[44:45], v[74:75], v[44:45]
	v_pk_fma_f32 v[32:33], v[32:33], v[64:65], v[42:43]
	v_pk_mul_f32 v[44:45], v[46:47], v[44:45]
	s_nop 0
	v_pk_fma_f32 v[34:35], v[34:35], v[66:67], v[44:45]
.LBB0_246:
	s_nop 0
	v_pk_mul_f32 v[42:43], v[48:49], v[34:35]
	v_pk_mul_f32 v[34:35], v[174:175], v[32:33]
	v_pk_mul_f32 v[38:39], v[48:49], v[38:39]
	v_pk_mul_f32 v[36:37], v[174:175], v[36:37]
	s_and_b64 vcc, exec, s[6:7]
	v_cvt_pk_bf16_f32 v32, v36, v37
	v_cvt_pk_bf16_f32 v33, v38, v39
	v_cvt_pk_bf16_f32 v34, v34, v35
	v_cvt_pk_bf16_f32 v35, v42, v43
	global_store_dwordx4 v[40:41], v[32:35], off offset:256 nt
	s_nop 1
	v_add_u32_e32 v34, 0xa0, v184
	s_cbranch_vccnz .LBB0_248
	v_add_u32_e32 v246, 0xb0, v184
	v_and_b32_e32 v246, s51, v246
	v_lshl_add_u32 v246, v246, 7, v176
	global_load_dwordx4 v[64:67], v246, s[14:15] offset:16
	global_load_dwordx4 v[80:83], v246, s[14:15]
	global_load_dwordx4 v[72:75], v246, s[14:15] offset:80
	global_load_dwordx4 v[84:87], v246, s[14:15] offset:64
.LBB0_248:
	s_and_b64 vcc, exec, s[6:7]
	s_cbranch_vccnz .LBB0_250
	ds_bpermute_b32 v32, v183, v28
	ds_bpermute_b32 v33, v183, v29
	ds_bpermute_b32 v36, v183, v30
	ds_bpermute_b32 v37, v183, v31
	v_mov_b32_e32 v38, v172
	v_mov_b32_e32 v39, v172
	s_waitcnt vmcnt(6) lgkmcnt(0)
	v_pk_mul_f32 v[32:33], v[152:153], v[32:33]
	v_pk_mul_f32 v[36:37], v[154:155], v[36:37]
	v_pk_mul_f32 v[32:33], v[172:173], v[32:33]
	v_pk_mul_f32 v[36:37], v[38:39], v[36:37]
	v_pk_fma_f32 v[28:29], v[28:29], v[156:157], v[32:33]
	v_pk_fma_f32 v[30:31], v[30:31], v[158:159], v[36:37]
	ds_bpermute_b32 v32, v183, v24
	ds_bpermute_b32 v33, v183, v25
	ds_bpermute_b32 v36, v183, v26
	ds_bpermute_b32 v37, v183, v27
	s_waitcnt lgkmcnt(2)
	v_pk_mul_f32 v[32:33], v[144:145], v[32:33]
	s_nop 0
	v_pk_mul_f32 v[32:33], v[172:173], v[32:33]
	s_waitcnt lgkmcnt(0)
	v_pk_mul_f32 v[36:37], v[146:147], v[36:37]
	v_pk_fma_f32 v[24:25], v[24:25], v[148:149], v[32:33]
	v_pk_mul_f32 v[36:37], v[38:39], v[36:37]
	s_nop 0
	v_pk_fma_f32 v[26:27], v[26:27], v[150:151], v[36:37]
.LBB0_250:
	v_mov_b32_e32 v32, v174
	v_mov_b32_e32 v33, v174
	v_pk_mul_f32 v[28:29], v[174:175], v[28:29]
	v_pk_mul_f32 v[24:25], v[174:175], v[24:25]
	v_pk_mul_f32 v[30:31], v[32:33], v[30:31]
	v_pk_mul_f32 v[36:37], v[32:33], v[26:27]
	v_cvt_pk_bf16_f32 v26, v28, v29
	v_cvt_pk_bf16_f32 v27, v30, v31
	v_cvt_pk_bf16_f32 v28, v24, v25
	v_mov_b64_e32 v[24:25], s[12:13]
	v_mad_i64_i32 v[24:25], s[28:29], v34, s88, v[24:25]
	v_lshl_add_u64 v[24:25], v[178:179], 1, v[24:25]
	s_and_b64 vcc, exec, s[6:7]
	v_cvt_pk_bf16_f32 v29, v36, v37
	global_store_dwordx4 v[24:25], v[26:29], off nt
	s_cbranch_vccnz .LBB0_252
	ds_bpermute_b32 v26, v183, v20
	ds_bpermute_b32 v27, v183, v21
	ds_bpermute_b32 v28, v183, v22
	ds_bpermute_b32 v29, v183, v23
	v_mov_b32_e32 v30, v172
	v_mov_b32_e32 v31, v172
	s_waitcnt lgkmcnt(0)
	v_pk_mul_f32 v[26:27], v[152:153], v[26:27]
	v_pk_mul_f32 v[28:29], v[154:155], v[28:29]
	v_pk_mul_f32 v[26:27], v[172:173], v[26:27]
	v_pk_mul_f32 v[28:29], v[30:31], v[28:29]
	v_pk_fma_f32 v[20:21], v[20:21], v[156:157], v[26:27]
	v_pk_fma_f32 v[22:23], v[22:23], v[158:159], v[28:29]
	ds_bpermute_b32 v26, v183, v16
	ds_bpermute_b32 v27, v183, v17
	ds_bpermute_b32 v28, v183, v18
	ds_bpermute_b32 v29, v183, v19
	s_waitcnt lgkmcnt(2)
	v_pk_mul_f32 v[26:27], v[144:145], v[26:27]
	s_nop 0
	v_pk_mul_f32 v[26:27], v[172:173], v[26:27]
	s_waitcnt lgkmcnt(0)
	v_pk_mul_f32 v[28:29], v[146:147], v[28:29]
	v_pk_fma_f32 v[16:17], v[16:17], v[148:149], v[26:27]
	v_pk_mul_f32 v[28:29], v[30:31], v[28:29]
	s_nop 0
	v_pk_fma_f32 v[18:19], v[18:19], v[150:151], v[28:29]

.LBB0_254:
	s_and_b64 vcc, exec, s[6:7]
	s_cbranch_vccnz .LBB0_256
	ds_bpermute_b32 v16, v183, v12
	ds_bpermute_b32 v17, v183, v13
	ds_bpermute_b32 v20, v183, v14
	ds_bpermute_b32 v21, v183, v15
	v_mov_b32_e32 v22, v172
	v_mov_b32_e32 v23, v172
	s_waitcnt vmcnt(2) lgkmcnt(0)
	v_pk_mul_f32 v[16:17], v[84:85], v[16:17]
	v_pk_mul_f32 v[20:21], v[86:87], v[20:21]
	v_pk_mul_f32 v[16:17], v[172:173], v[16:17]
	v_pk_mul_f32 v[20:21], v[22:23], v[20:21]
	v_pk_fma_f32 v[12:13], v[12:13], v[80:81], v[16:17]
	v_pk_fma_f32 v[14:15], v[14:15], v[82:83], v[20:21]
	ds_bpermute_b32 v16, v183, v8
	ds_bpermute_b32 v17, v183, v9
	ds_bpermute_b32 v20, v183, v10
	ds_bpermute_b32 v21, v183, v11
	s_waitcnt lgkmcnt(2)
	v_pk_mul_f32 v[16:17], v[72:73], v[16:17]
	s_nop 0
	v_pk_mul_f32 v[16:17], v[172:173], v[16:17]
	s_waitcnt lgkmcnt(0)
	v_pk_mul_f32 v[20:21], v[74:75], v[20:21]
	v_pk_fma_f32 v[8:9], v[8:9], v[64:65], v[16:17]
	v_pk_mul_f32 v[20:21], v[22:23], v[20:21]
	s_nop 0
	v_pk_fma_f32 v[10:11], v[10:11], v[66:67], v[20:21]
.LBB0_256:
	v_mov_b32_e32 v16, v174
	v_mov_b32_e32 v17, v174
	v_pk_mul_f32 v[12:13], v[174:175], v[12:13]
	v_pk_mul_f32 v[8:9], v[174:175], v[8:9]
	v_pk_mul_f32 v[14:15], v[16:17], v[14:15]
	v_pk_mul_f32 v[20:21], v[16:17], v[10:11]
	v_cvt_pk_bf16_f32 v10, v12, v13
	v_cvt_pk_bf16_f32 v11, v14, v15
	v_cvt_pk_bf16_f32 v12, v8, v9
	v_mov_b64_e32 v[8:9], s[12:13]
	v_mad_i64_i32 v[8:9], s[28:29], v18, s88, v[8:9]
	v_lshl_add_u64 v[8:9], v[178:179], 1, v[8:9]
	s_and_b64 vcc, exec, s[6:7]
	v_cvt_pk_bf16_f32 v13, v20, v21
	global_store_dwordx4 v[8:9], v[10:13], off nt
	s_cbranch_vccnz .LBB0_258
	ds_bpermute_b32 v10, v183, v4
	ds_bpermute_b32 v11, v183, v5
	ds_bpermute_b32 v12, v183, v6
	ds_bpermute_b32 v13, v183, v7
	v_mov_b32_e32 v14, v172
	v_mov_b32_e32 v15, v172
	s_waitcnt lgkmcnt(0)
	v_pk_mul_f32 v[10:11], v[84:85], v[10:11]
	v_pk_mul_f32 v[12:13], v[86:87], v[12:13]
	v_pk_mul_f32 v[10:11], v[172:173], v[10:11]
	v_pk_mul_f32 v[12:13], v[14:15], v[12:13]
	v_pk_fma_f32 v[4:5], v[4:5], v[80:81], v[10:11]
	v_pk_fma_f32 v[6:7], v[6:7], v[82:83], v[12:13]
	ds_bpermute_b32 v10, v183, v0
	ds_bpermute_b32 v11, v183, v1
	ds_bpermute_b32 v12, v183, v2
	ds_bpermute_b32 v13, v183, v3
	s_waitcnt lgkmcnt(2)
	v_pk_mul_f32 v[10:11], v[72:73], v[10:11]
	s_nop 0
	v_pk_mul_f32 v[10:11], v[172:173], v[10:11]
	s_waitcnt lgkmcnt(0)
	v_pk_mul_f32 v[12:13], v[74:75], v[12:13]
	v_pk_fma_f32 v[0:1], v[0:1], v[64:65], v[10:11]
	v_pk_mul_f32 v[12:13], v[14:15], v[12:13]
	s_nop 0
	v_pk_fma_f32 v[2:3], v[2:3], v[66:67], v[12:13]

.LBB0_643:
	s_add_u32 s6, s4, 0xfff80080
	s_addc_u32 s7, s5, -1
	s_add_i32 s50, 0, 0x10000
	s_cmp_eq_u32 s49, 28
	s_cselect_b32 s9, s1, s7
	s_cselect_b32 s8, s23, s6
	v_add_u32_e32 v148, s50, v151
	s_cselect_b32 s7, s21, s43
	s_cselect_b32 s6, s33, s42
	s_add_i32 s53, 0, 0x14000
	ds_read_b128 v[140:143], v148
	ds_read_b128 v[144:147], v148 offset:1024
	ds_read_b128 v[154:157], v148 offset:2048
	ds_read_b128 v[158:161], v148 offset:3072
	v_add_u32_e32 v148, s53, v151
	ds_read_b128 v[162:165], v148
	ds_read_b128 v[166:169], v148 offset:1024
	ds_read_b128 v[170:173], v148 offset:2048
	ds_read_b128 v[174:177], v148 offset:3072
	v_lshl_add_u64 v[148:149], s[4:5], 0, v[136:137]
	s_add_i32 m0, s11, 0xc000
	ds_read_b128 v[178:181], v152
	ds_read_b128 v[182:185], v152 offset:1024
	ds_read_b128 v[186:189], v152 offset:2048
	ds_read_b128 v[190:193], v152 offset:3072
	ds_read_b128 v[194:197], v152 offset:4096
	ds_read_b128 v[202:205], v152 offset:5120
	ds_read_b128 v[206:209], v152 offset:6144
	ds_read_b128 v[212:215], v152 offset:7168
	global_load_lds_dwordx4 v[148:149], off
	v_lshl_add_u64 v[148:149], s[4:5], 0, v[138:139]
	s_add_i32 m0, s11, 0xe000
	s_nop 0
	global_load_lds_dwordx4 v[148:149], off
	s_waitcnt vmcnt(8)
	s_waitcnt lgkmcnt(0)
	s_setprio 1
	s_barrier
	v_mfma_f32_16x16x32_bf16 v[124:127], v[140:143], v[178:181], v[124:127]
	v_mfma_f32_16x16x32_bf16 v[120:123], v[154:157], v[178:181], v[120:123]
	v_mfma_f32_16x16x32_bf16 v[108:111], v[140:143], v[186:189], v[108:111]
	v_mfma_f32_16x16x32_bf16 v[104:107], v[154:157], v[186:189], v[104:107]
	v_mfma_f32_16x16x32_bf16 v[92:95], v[140:143], v[194:197], v[92:95]
	v_mfma_f32_16x16x32_bf16 v[88:91], v[154:157], v[194:197], v[88:91]
	v_mfma_f32_16x16x32_bf16 v[76:79], v[140:143], v[206:209], v[76:79]
	v_mfma_f32_16x16x32_bf16 v[72:75], v[154:157], v[206:209], v[72:75]
	v_mfma_f32_16x16x32_bf16 v[124:127], v[144:147], v[182:185], v[124:127]
	v_mfma_f32_16x16x32_bf16 v[120:123], v[158:161], v[182:185], v[120:123]
	v_mfma_f32_16x16x32_bf16 v[108:111], v[144:147], v[190:193], v[108:111]
	v_mfma_f32_16x16x32_bf16 v[104:107], v[158:161], v[190:193], v[104:107]
	v_mfma_f32_16x16x32_bf16 v[92:95], v[144:147], v[202:205], v[92:95]
	v_mfma_f32_16x16x32_bf16 v[88:91], v[158:161], v[202:205], v[88:91]
	v_mfma_f32_16x16x32_bf16 v[76:79], v[144:147], v[212:215], v[76:79]
	v_mfma_f32_16x16x32_bf16 v[72:75], v[158:161], v[212:215], v[72:75]
	s_setprio 0
	s_setprio 1
	v_mfma_f32_16x16x32_bf16 v[116:119], v[162:165], v[178:181], v[116:119]
	v_mfma_f32_16x16x32_bf16 v[112:115], v[170:173], v[178:181], v[112:115]
	v_mfma_f32_16x16x32_bf16 v[100:103], v[162:165], v[186:189], v[100:103]
	v_mfma_f32_16x16x32_bf16 v[96:99], v[170:173], v[186:189], v[96:99]
	v_mfma_f32_16x16x32_bf16 v[84:87], v[162:165], v[194:197], v[84:87]
	v_mfma_f32_16x16x32_bf16 v[80:83], v[170:173], v[194:197], v[80:83]
	v_mfma_f32_16x16x32_bf16 v[68:71], v[162:165], v[206:209], v[68:71]
	v_mfma_f32_16x16x32_bf16 v[64:67], v[170:173], v[206:209], v[64:67]
	v_mfma_f32_16x16x32_bf16 v[116:119], v[166:169], v[182:185], v[116:119]
	v_mfma_f32_16x16x32_bf16 v[112:115], v[174:177], v[182:185], v[112:115]
	v_mfma_f32_16x16x32_bf16 v[100:103], v[166:169], v[190:193], v[100:103]
	v_mfma_f32_16x16x32_bf16 v[96:99], v[174:177], v[190:193], v[96:99]
	v_mfma_f32_16x16x32_bf16 v[84:87], v[166:169], v[202:205], v[84:87]
	v_mfma_f32_16x16x32_bf16 v[80:83], v[174:177], v[202:205], v[80:83]
	v_mfma_f32_16x16x32_bf16 v[68:71], v[166:169], v[212:215], v[68:71]
	v_mfma_f32_16x16x32_bf16 v[64:67], v[174:177], v[212:215], v[64:67]
	s_barrier
	s_setprio 0
	s_add_i32 s50, s50, s35
	v_lshl_add_u64 v[148:149], s[6:7], 0, v[130:131]
	s_mov_b32 m0, s50
	ds_read_b128 v[178:181], v152 offset:16384
	ds_read_b128 v[182:185], v152 offset:17408
	ds_read_b128 v[186:189], v152 offset:18432
	ds_read_b128 v[190:193], v152 offset:19456
	ds_read_b128 v[194:197], v152 offset:20480
	ds_read_b128 v[202:205], v152 offset:21504
	ds_read_b128 v[206:209], v152 offset:22528
	ds_read_b128 v[212:215], v152 offset:23552
	global_load_lds_dwordx4 v[148:149], off
	s_add_i32 m0, s50, 0x2000
	s_add_u32 s50, s6, 0x80000
	v_lshl_add_u64 v[198:199], s[6:7], 0, v[134:135]
	s_addc_u32 s51, s7, 0
	s_add_i32 s53, s53, s35
	global_load_lds_dwordx4 v[198:199], off
	v_lshl_add_u64 v[216:217], s[50:51], 0, v[130:131]
	s_mov_b32 m0, s53
	v_lshl_add_u64 v[218:219], s[8:9], 0, v[132:133]
	global_load_lds_dwordx4 v[216:217], off
	v_lshl_add_u64 v[216:217], s[50:51], 0, v[134:135]
	s_add_i32 m0, s53, 0x2000
	s_nop 0
	global_load_lds_dwordx4 v[216:217], off
	v_lshl_add_u64 v[216:217], s[8:9], 0, v[128:129]
	s_mov_b32 m0, s11
	s_nop 0
	global_load_lds_dwordx4 v[216:217], off
	s_mov_b32 m0, s36
	s_nop 0
	global_load_lds_dwordx4 v[218:219], off
	s_waitcnt vmcnt(8)
	s_waitcnt lgkmcnt(0)
	s_setprio 1
	s_barrier
	v_mfma_f32_16x16x32_bf16 v[60:63], v[140:143], v[178:181], v[60:63]
	v_mfma_f32_16x16x32_bf16 v[56:59], v[154:157], v[178:181], v[56:59]
	v_mfma_f32_16x16x32_bf16 v[44:47], v[140:143], v[186:189], v[44:47]
	v_mfma_f32_16x16x32_bf16 v[40:43], v[154:157], v[186:189], v[40:43]
	v_mfma_f32_16x16x32_bf16 v[28:31], v[140:143], v[194:197], v[28:31]
	v_mfma_f32_16x16x32_bf16 v[24:27], v[154:157], v[194:197], v[24:27]
	v_mfma_f32_16x16x32_bf16 v[12:15], v[140:143], v[206:209], v[12:15]
	v_mfma_f32_16x16x32_bf16 v[8:11], v[154:157], v[206:209], v[8:11]
	v_mfma_f32_16x16x32_bf16 v[60:63], v[144:147], v[182:185], v[60:63]
	v_mfma_f32_16x16x32_bf16 v[56:59], v[158:161], v[182:185], v[56:59]
	v_mfma_f32_16x16x32_bf16 v[44:47], v[144:147], v[190:193], v[44:47]
	v_mfma_f32_16x16x32_bf16 v[40:43], v[158:161], v[190:193], v[40:43]
	v_mfma_f32_16x16x32_bf16 v[28:31], v[144:147], v[202:205], v[28:31]
	v_mfma_f32_16x16x32_bf16 v[24:27], v[158:161], v[202:205], v[24:27]
	v_mfma_f32_16x16x32_bf16 v[12:15], v[144:147], v[212:215], v[12:15]
	v_mfma_f32_16x16x32_bf16 v[8:11], v[158:161], v[212:215], v[8:11]
	s_setprio 0
	s_setprio 1
	v_mfma_f32_16x16x32_bf16 v[52:55], v[162:165], v[178:181], v[52:55]
	v_mfma_f32_16x16x32_bf16 v[48:51], v[170:173], v[178:181], v[48:51]
	v_mfma_f32_16x16x32_bf16 v[36:39], v[162:165], v[186:189], v[36:39]
	v_mfma_f32_16x16x32_bf16 v[32:35], v[170:173], v[186:189], v[32:35]
	v_mfma_f32_16x16x32_bf16 v[20:23], v[162:165], v[194:197], v[20:23]
	v_mfma_f32_16x16x32_bf16 v[16:19], v[170:173], v[194:197], v[16:19]
	v_mfma_f32_16x16x32_bf16 v[4:7], v[162:165], v[206:209], v[4:7]
	v_mfma_f32_16x16x32_bf16 v[0:3], v[170:173], v[206:209], v[0:3]
	v_mfma_f32_16x16x32_bf16 v[52:55], v[166:169], v[182:185], v[52:55]
	v_mfma_f32_16x16x32_bf16 v[48:51], v[174:177], v[182:185], v[48:51]
	v_mfma_f32_16x16x32_bf16 v[36:39], v[166:169], v[190:193], v[36:39]
	v_mfma_f32_16x16x32_bf16 v[32:35], v[174:177], v[190:193], v[32:35]
	v_mfma_f32_16x16x32_bf16 v[20:23], v[166:169], v[202:205], v[20:23]
	v_mfma_f32_16x16x32_bf16 v[16:19], v[174:177], v[202:205], v[16:19]
	v_mfma_f32_16x16x32_bf16 v[4:7], v[166:169], v[212:215], v[4:7]
	v_mfma_f32_16x16x32_bf16 v[0:3], v[174:177], v[212:215], v[0:3]
	s_barrier
	s_setprio 0
	s_add_i32 s50, 0, 0x18000
	v_add_u32_e32 v153, s50, v151
	s_add_i32 s51, 0, 0x1c000
	ds_read_b128 v[140:143], v153
	ds_read_b128 v[144:147], v153 offset:1024
	ds_read_b128 v[154:157], v153 offset:2048
	ds_read_b128 v[158:161], v153 offset:3072
	v_add_u32_e32 v153, s51, v151
	ds_read_b128 v[162:165], v153
	ds_read_b128 v[166:169], v153 offset:1024
	ds_read_b128 v[170:173], v153 offset:2048
	ds_read_b128 v[174:177], v153 offset:3072
	s_add_u32 s8, s8, 0x80000
	s_addc_u32 s9, s9, 0
	s_mov_b32 m0, s37
	v_lshl_add_u64 v[220:221], s[8:9], 0, v[128:129]
	ds_read_b128 v[178:181], v152 offset:32768
	ds_read_b128 v[182:185], v152 offset:33792
	ds_read_b128 v[186:189], v152 offset:34816
	ds_read_b128 v[190:193], v152 offset:35840
	ds_read_b128 v[194:197], v152 offset:36864
	ds_read_b128 v[202:205], v152 offset:37888
	ds_read_b128 v[206:209], v152 offset:38912
	ds_read_b128 v[212:215], v152 offset:39936
	global_load_lds_dwordx4 v[220:221], off
	v_lshl_add_u64 v[220:221], s[8:9], 0, v[132:133]
	s_mov_b32 m0, s38
	s_nop 0
	global_load_lds_dwordx4 v[220:221], off
	s_waitcnt vmcnt(8)
	s_waitcnt lgkmcnt(0)
	s_setprio 1
	s_barrier
	v_mfma_f32_16x16x32_bf16 v[124:127], v[140:143], v[178:181], v[124:127]
	v_mfma_f32_16x16x32_bf16 v[120:123], v[154:157], v[178:181], v[120:123]
	v_mfma_f32_16x16x32_bf16 v[108:111], v[140:143], v[186:189], v[108:111]
	v_mfma_f32_16x16x32_bf16 v[104:107], v[154:157], v[186:189], v[104:107]
	v_mfma_f32_16x16x32_bf16 v[92:95], v[140:143], v[194:197], v[92:95]
	v_mfma_f32_16x16x32_bf16 v[88:91], v[154:157], v[194:197], v[88:91]
	v_mfma_f32_16x16x32_bf16 v[76:79], v[140:143], v[206:209], v[76:79]
	v_mfma_f32_16x16x32_bf16 v[72:75], v[154:157], v[206:209], v[72:75]
	v_mfma_f32_16x16x32_bf16 v[124:127], v[144:147], v[182:185], v[124:127]
	v_mfma_f32_16x16x32_bf16 v[120:123], v[158:161], v[182:185], v[120:123]
	v_mfma_f32_16x16x32_bf16 v[108:111], v[144:147], v[190:193], v[108:111]
	v_mfma_f32_16x16x32_bf16 v[104:107], v[158:161], v[190:193], v[104:107]
	v_mfma_f32_16x16x32_bf16 v[92:95], v[144:147], v[202:205], v[92:95]
	v_mfma_f32_16x16x32_bf16 v[88:91], v[158:161], v[202:205], v[88:91]
	v_mfma_f32_16x16x32_bf16 v[76:79], v[144:147], v[212:215], v[76:79]
	v_mfma_f32_16x16x32_bf16 v[72:75], v[158:161], v[212:215], v[72:75]
	s_setprio 0
	s_setprio 1
	v_mfma_f32_16x16x32_bf16 v[116:119], v[162:165], v[178:181], v[116:119]
	v_mfma_f32_16x16x32_bf16 v[112:115], v[170:173], v[178:181], v[112:115]
	v_mfma_f32_16x16x32_bf16 v[100:103], v[162:165], v[186:189], v[100:103]
	v_mfma_f32_16x16x32_bf16 v[96:99], v[170:173], v[186:189], v[96:99]
	v_mfma_f32_16x16x32_bf16 v[84:87], v[162:165], v[194:197], v[84:87]
	v_mfma_f32_16x16x32_bf16 v[80:83], v[170:173], v[194:197], v[80:83]
	v_mfma_f32_16x16x32_bf16 v[68:71], v[162:165], v[206:209], v[68:71]
	v_mfma_f32_16x16x32_bf16 v[64:67], v[170:173], v[206:209], v[64:67]
	v_mfma_f32_16x16x32_bf16 v[116:119], v[166:169], v[182:185], v[116:119]
	v_mfma_f32_16x16x32_bf16 v[112:115], v[174:177], v[182:185], v[112:115]
	v_mfma_f32_16x16x32_bf16 v[100:103], v[166:169], v[190:193], v[100:103]
	v_mfma_f32_16x16x32_bf16 v[96:99], v[174:177], v[190:193], v[96:99]
	v_mfma_f32_16x16x32_bf16 v[84:87], v[166:169], v[202:205], v[84:87]
	v_mfma_f32_16x16x32_bf16 v[80:83], v[174:177], v[202:205], v[80:83]
	v_mfma_f32_16x16x32_bf16 v[68:71], v[166:169], v[212:215], v[68:71]
	v_mfma_f32_16x16x32_bf16 v[64:67], v[174:177], v[212:215], v[64:67]
	s_barrier
	s_setprio 0
	s_add_i32 s8, s50, s35
	v_lshl_add_u64 v[148:149], v[148:149], 0, s[64:65]
	s_mov_b32 m0, s8
	ds_read_b128 v[178:181], v152 offset:49152
	ds_read_b128 v[182:185], v152 offset:50176
	ds_read_b128 v[186:189], v152 offset:51200
	ds_read_b128 v[190:193], v152 offset:52224
	ds_read_b128 v[194:197], v152 offset:53248
	ds_read_b128 v[202:205], v152 offset:54272
	ds_read_b128 v[206:209], v152 offset:55296
	ds_read_b128 v[212:215], v152 offset:56320
	global_load_lds_dwordx4 v[148:149], off
	s_add_i32 m0, s8, 0x2000
	s_add_u32 s6, s6, 0x80080
	v_lshl_add_u64 v[148:149], v[198:199], 0, s[64:65]
	s_addc_u32 s7, s7, 0
	s_add_i32 s8, s51, s35
	global_load_lds_dwordx4 v[148:149], off
	v_lshl_add_u64 v[148:149], s[6:7], 0, v[130:131]
	s_mov_b32 m0, s8
	s_nop 0
	global_load_lds_dwordx4 v[148:149], off
	v_lshl_add_u64 v[148:149], s[6:7], 0, v[134:135]
	s_add_i32 m0, s8, 0x2000
	s_nop 0
	global_load_lds_dwordx4 v[148:149], off
	v_lshl_add_u64 v[148:149], v[216:217], 0, s[64:65]
	s_mov_b32 m0, s40
	s_nop 0
	global_load_lds_dwordx4 v[148:149], off
	v_lshl_add_u64 v[148:149], v[218:219], 0, s[64:65]
	s_mov_b32 m0, s41
	s_nop 0
	global_load_lds_dwordx4 v[148:149], off
	s_waitcnt vmcnt(8)
	s_waitcnt lgkmcnt(0)
	s_setprio 1
	s_barrier
	v_mfma_f32_16x16x32_bf16 v[60:63], v[140:143], v[178:181], v[60:63]
	v_mfma_f32_16x16x32_bf16 v[56:59], v[154:157], v[178:181], v[56:59]
	v_mfma_f32_16x16x32_bf16 v[44:47], v[140:143], v[186:189], v[44:47]
	v_mfma_f32_16x16x32_bf16 v[40:43], v[154:157], v[186:189], v[40:43]
	v_mfma_f32_16x16x32_bf16 v[28:31], v[140:143], v[194:197], v[28:31]
	v_mfma_f32_16x16x32_bf16 v[24:27], v[154:157], v[194:197], v[24:27]
	v_mfma_f32_16x16x32_bf16 v[12:15], v[140:143], v[206:209], v[12:15]
	v_mfma_f32_16x16x32_bf16 v[8:11], v[154:157], v[206:209], v[8:11]
	v_mfma_f32_16x16x32_bf16 v[60:63], v[144:147], v[182:185], v[60:63]
	v_mfma_f32_16x16x32_bf16 v[56:59], v[158:161], v[182:185], v[56:59]
	v_mfma_f32_16x16x32_bf16 v[44:47], v[144:147], v[190:193], v[44:47]
	v_mfma_f32_16x16x32_bf16 v[40:43], v[158:161], v[190:193], v[40:43]
	v_mfma_f32_16x16x32_bf16 v[28:31], v[144:147], v[202:205], v[28:31]
	v_mfma_f32_16x16x32_bf16 v[24:27], v[158:161], v[202:205], v[24:27]
	v_mfma_f32_16x16x32_bf16 v[12:15], v[144:147], v[212:215], v[12:15]
	v_mfma_f32_16x16x32_bf16 v[8:11], v[158:161], v[212:215], v[8:11]
	s_setprio 0
	s_setprio 1
	v_mfma_f32_16x16x32_bf16 v[52:55], v[162:165], v[178:181], v[52:55]
	v_mfma_f32_16x16x32_bf16 v[48:51], v[170:173], v[178:181], v[48:51]
	v_mfma_f32_16x16x32_bf16 v[36:39], v[162:165], v[186:189], v[36:39]
	v_mfma_f32_16x16x32_bf16 v[32:35], v[170:173], v[186:189], v[32:35]
	v_mfma_f32_16x16x32_bf16 v[20:23], v[162:165], v[194:197], v[20:23]
	v_mfma_f32_16x16x32_bf16 v[16:19], v[170:173], v[194:197], v[16:19]
	v_mfma_f32_16x16x32_bf16 v[4:7], v[162:165], v[206:209], v[4:7]
	v_mfma_f32_16x16x32_bf16 v[0:3], v[170:173], v[206:209], v[0:3]
	v_mfma_f32_16x16x32_bf16 v[52:55], v[166:169], v[182:185], v[52:55]
	v_mfma_f32_16x16x32_bf16 v[48:51], v[174:177], v[182:185], v[48:51]
	v_mfma_f32_16x16x32_bf16 v[36:39], v[166:169], v[190:193], v[36:39]
	v_mfma_f32_16x16x32_bf16 v[32:35], v[174:177], v[190:193], v[32:35]
	v_mfma_f32_16x16x32_bf16 v[20:23], v[166:169], v[202:205], v[20:23]
	v_mfma_f32_16x16x32_bf16 v[16:19], v[174:177], v[202:205], v[16:19]
	v_mfma_f32_16x16x32_bf16 v[4:7], v[166:169], v[212:215], v[4:7]
	v_mfma_f32_16x16x32_bf16 v[0:3], v[174:177], v[212:215], v[0:3]
	s_barrier
	s_setprio 0
	s_add_i32 s49, s49, 2
	s_add_u32 s4, s4, 0x100
	s_addc_u32 s5, s5, 0
	s_add_u32 s42, s42, 0x100
	s_addc_u32 s43, s43, 0
	s_cmp_gt_u32 s49, 29
	s_cbranch_scc0 .LBB0_643
	s_and_b64 vcc, exec, s[18:19]
	s_cbranch_vccz .LBB0_646
	s_barrier

.LBB0_974:
	s_add_i32 s88, s68, 2
	s_add_u32 s89, s4, 0x80
	s_addc_u32 s69, s5, 0
	s_add_i32 s92, 0, 0x10000
	s_cmp_eq_u32 s84, s68
	s_cselect_b32 s69, s63, s69
	s_cselect_b32 s68, s62, s89
	s_cselect_b32 s91, s67, s71
	s_cselect_b32 s90, s66, s70
	s_add_i32 s89, 0, 0x14000
	v_add_u32_e32 v152, s92, v181
	v_add_u32_e32 v168, s89, v181
	ds_read_b128 v[128:131], v152
	ds_read_b128 v[132:135], v152 offset:1024
	ds_read_b128 v[136:139], v152 offset:2048
	ds_read_b128 v[152:155], v152 offset:3072
	ds_read_b128 v[156:159], v168
	ds_read_b128 v[160:163], v168 offset:1024
	ds_read_b128 v[164:167], v168 offset:2048
	ds_read_b128 v[168:171], v168 offset:3072
	v_lshl_add_u64 v[212:213], s[4:5], 0, v[148:149]
	s_add_i32 m0, s76, 0xc000
	ds_read_b128 v[172:175], v182
	ds_read_b128 v[176:179], v182 offset:1024
	ds_read_b128 v[184:187], v182 offset:2048
	ds_read_b128 v[188:191], v182 offset:3072
	ds_read_b128 v[192:195], v182 offset:4096
	ds_read_b128 v[196:199], v182 offset:5120
	ds_read_b128 v[202:205], v182 offset:6144
	ds_read_b128 v[206:209], v182 offset:7168
	global_load_lds_dwordx4 v[212:213], off
	v_lshl_add_u64 v[212:213], s[4:5], 0, v[150:151]
	s_add_i32 m0, s76, 0xe000
	s_nop 0
	global_load_lds_dwordx4 v[212:213], off
	s_waitcnt vmcnt(8)
	s_waitcnt lgkmcnt(0)
	s_setprio 1
	s_barrier
	v_mfma_f32_16x16x32_bf16 v[124:127], v[128:131], v[172:175], v[124:127]
	v_mfma_f32_16x16x32_bf16 v[120:123], v[136:139], v[172:175], v[120:123]
	v_mfma_f32_16x16x32_bf16 v[116:119], v[128:131], v[184:187], v[116:119]
	v_mfma_f32_16x16x32_bf16 v[112:115], v[136:139], v[184:187], v[112:115]
	v_mfma_f32_16x16x32_bf16 v[108:111], v[128:131], v[192:195], v[108:111]
	v_mfma_f32_16x16x32_bf16 v[104:107], v[136:139], v[192:195], v[104:107]
	v_mfma_f32_16x16x32_bf16 v[100:103], v[128:131], v[202:205], v[100:103]
	v_mfma_f32_16x16x32_bf16 v[96:99], v[136:139], v[202:205], v[96:99]
	v_mfma_f32_16x16x32_bf16 v[124:127], v[132:135], v[176:179], v[124:127]
	v_mfma_f32_16x16x32_bf16 v[120:123], v[152:155], v[176:179], v[120:123]
	v_mfma_f32_16x16x32_bf16 v[116:119], v[132:135], v[188:191], v[116:119]
	v_mfma_f32_16x16x32_bf16 v[112:115], v[152:155], v[188:191], v[112:115]
	v_mfma_f32_16x16x32_bf16 v[108:111], v[132:135], v[196:199], v[108:111]
	v_mfma_f32_16x16x32_bf16 v[104:107], v[152:155], v[196:199], v[104:107]
	v_mfma_f32_16x16x32_bf16 v[100:103], v[132:135], v[206:209], v[100:103]
	v_mfma_f32_16x16x32_bf16 v[96:99], v[152:155], v[206:209], v[96:99]
	s_setprio 0
	s_setprio 1
	v_mfma_f32_16x16x32_bf16 v[92:95], v[156:159], v[172:175], v[92:95]
	v_mfma_f32_16x16x32_bf16 v[88:91], v[164:167], v[172:175], v[88:91]
	v_mfma_f32_16x16x32_bf16 v[84:87], v[156:159], v[184:187], v[84:87]
	v_mfma_f32_16x16x32_bf16 v[80:83], v[164:167], v[184:187], v[80:83]
	v_mfma_f32_16x16x32_bf16 v[76:79], v[156:159], v[192:195], v[76:79]
	v_mfma_f32_16x16x32_bf16 v[72:75], v[164:167], v[192:195], v[72:75]
	v_mfma_f32_16x16x32_bf16 v[68:71], v[156:159], v[202:205], v[68:71]
	v_mfma_f32_16x16x32_bf16 v[64:67], v[164:167], v[202:205], v[64:67]
	v_mfma_f32_16x16x32_bf16 v[92:95], v[160:163], v[176:179], v[92:95]
	v_mfma_f32_16x16x32_bf16 v[88:91], v[168:171], v[176:179], v[88:91]
	v_mfma_f32_16x16x32_bf16 v[84:87], v[160:163], v[188:191], v[84:87]
	v_mfma_f32_16x16x32_bf16 v[80:83], v[168:171], v[188:191], v[80:83]
	v_mfma_f32_16x16x32_bf16 v[76:79], v[160:163], v[196:199], v[76:79]
	v_mfma_f32_16x16x32_bf16 v[72:75], v[168:171], v[196:199], v[72:75]
	v_mfma_f32_16x16x32_bf16 v[68:71], v[160:163], v[206:209], v[68:71]
	v_mfma_f32_16x16x32_bf16 v[64:67], v[168:171], v[206:209], v[64:67]
	s_barrier
	s_setprio 0
	s_add_i32 s92, s92, s72
	v_lshl_add_u64 v[212:213], s[90:91], 0, v[142:143]
	s_mov_b32 m0, s92
	ds_read_b128 v[172:175], v182 offset:16384
	ds_read_b128 v[176:179], v182 offset:17408
	ds_read_b128 v[184:187], v182 offset:18432
	ds_read_b128 v[188:191], v182 offset:19456
	ds_read_b128 v[192:195], v182 offset:20480
	ds_read_b128 v[196:199], v182 offset:21504
	ds_read_b128 v[202:205], v182 offset:22528
	ds_read_b128 v[206:209], v182 offset:23552
	global_load_lds_dwordx4 v[212:213], off
	s_add_i32 m0, s92, 0x2000
	v_lshl_add_u64 v[214:215], s[90:91], 0, v[146:147]
	s_add_u32 s90, s90, s56
	s_addc_u32 s91, s91, 0
	s_add_i32 s89, s89, s72
	global_load_lds_dwordx4 v[214:215], off
	v_lshl_add_u64 v[216:217], s[90:91], 0, v[142:143]
	s_mov_b32 m0, s89
	v_lshl_add_u64 v[218:219], s[90:91], 0, v[146:147]
	global_load_lds_dwordx4 v[216:217], off
	s_add_i32 m0, s89, 0x2000
	v_lshl_add_u64 v[220:221], s[68:69], 0, v[140:141]
	global_load_lds_dwordx4 v[218:219], off
	s_mov_b32 m0, s76
	v_lshl_add_u64 v[222:223], s[68:69], 0, v[144:145]
	global_load_lds_dwordx4 v[220:221], off
	s_mov_b32 m0, s77
	s_nop 0
	global_load_lds_dwordx4 v[222:223], off
	s_waitcnt vmcnt(8)
	s_waitcnt lgkmcnt(0)
	s_setprio 1
	s_barrier
	v_mfma_f32_16x16x32_bf16 v[60:63], v[128:131], v[172:175], v[60:63]
	v_mfma_f32_16x16x32_bf16 v[56:59], v[136:139], v[172:175], v[56:59]
	v_mfma_f32_16x16x32_bf16 v[52:55], v[128:131], v[184:187], v[52:55]
	v_mfma_f32_16x16x32_bf16 v[48:51], v[136:139], v[184:187], v[48:51]
	v_mfma_f32_16x16x32_bf16 v[44:47], v[128:131], v[192:195], v[44:47]
	v_mfma_f32_16x16x32_bf16 v[40:43], v[136:139], v[192:195], v[40:43]
	v_mfma_f32_16x16x32_bf16 v[36:39], v[128:131], v[202:205], v[36:39]
	v_mfma_f32_16x16x32_bf16 v[32:35], v[136:139], v[202:205], v[32:35]
	v_mfma_f32_16x16x32_bf16 v[60:63], v[132:135], v[176:179], v[60:63]
	v_mfma_f32_16x16x32_bf16 v[56:59], v[152:155], v[176:179], v[56:59]
	v_mfma_f32_16x16x32_bf16 v[52:55], v[132:135], v[188:191], v[52:55]
	v_mfma_f32_16x16x32_bf16 v[48:51], v[152:155], v[188:191], v[48:51]
	v_mfma_f32_16x16x32_bf16 v[44:47], v[132:135], v[196:199], v[44:47]
	v_mfma_f32_16x16x32_bf16 v[40:43], v[152:155], v[196:199], v[40:43]
	v_mfma_f32_16x16x32_bf16 v[36:39], v[132:135], v[206:209], v[36:39]
	v_mfma_f32_16x16x32_bf16 v[32:35], v[152:155], v[206:209], v[32:35]
	s_setprio 0
	s_setprio 1
	v_mfma_f32_16x16x32_bf16 v[28:31], v[156:159], v[172:175], v[28:31]
	v_mfma_f32_16x16x32_bf16 v[24:27], v[164:167], v[172:175], v[24:27]
	v_mfma_f32_16x16x32_bf16 v[20:23], v[156:159], v[184:187], v[20:23]
	v_mfma_f32_16x16x32_bf16 v[16:19], v[164:167], v[184:187], v[16:19]
	v_mfma_f32_16x16x32_bf16 v[12:15], v[156:159], v[192:195], v[12:15]
	v_mfma_f32_16x16x32_bf16 v[8:11], v[164:167], v[192:195], v[8:11]
	v_mfma_f32_16x16x32_bf16 v[4:7], v[156:159], v[202:205], v[4:7]
	v_mfma_f32_16x16x32_bf16 v[0:3], v[164:167], v[202:205], v[0:3]
	v_mfma_f32_16x16x32_bf16 v[28:31], v[160:163], v[176:179], v[28:31]
	v_mfma_f32_16x16x32_bf16 v[24:27], v[168:171], v[176:179], v[24:27]
	v_mfma_f32_16x16x32_bf16 v[20:23], v[160:163], v[188:191], v[20:23]
	v_mfma_f32_16x16x32_bf16 v[16:19], v[168:171], v[188:191], v[16:19]
	v_mfma_f32_16x16x32_bf16 v[12:15], v[160:163], v[196:199], v[12:15]
	v_mfma_f32_16x16x32_bf16 v[8:11], v[168:171], v[196:199], v[8:11]
	v_mfma_f32_16x16x32_bf16 v[4:7], v[160:163], v[206:209], v[4:7]
	v_mfma_f32_16x16x32_bf16 v[0:3], v[168:171], v[206:209], v[0:3]
	s_barrier
	s_setprio 0
	s_add_i32 s89, 0, 0x18000
	s_add_i32 s90, 0, 0x1c000
	v_add_u32_e32 v152, s89, v181
	v_add_u32_e32 v168, s90, v181
	ds_read_b128 v[128:131], v152
	ds_read_b128 v[132:135], v152 offset:1024
	ds_read_b128 v[136:139], v152 offset:2048
	ds_read_b128 v[152:155], v152 offset:3072
	ds_read_b128 v[156:159], v168
	ds_read_b128 v[160:163], v168 offset:1024
	ds_read_b128 v[164:167], v168 offset:2048
	ds_read_b128 v[168:171], v168 offset:3072
	s_add_u32 s68, s68, s56
	s_addc_u32 s69, s69, 0
	s_mov_b32 m0, s78
	v_lshl_add_u64 v[224:225], s[68:69], 0, v[140:141]
	ds_read_b128 v[172:175], v182 offset:32768
	ds_read_b128 v[176:179], v182 offset:33792
	ds_read_b128 v[184:187], v182 offset:34816
	ds_read_b128 v[188:191], v182 offset:35840
	ds_read_b128 v[192:195], v182 offset:36864
	ds_read_b128 v[196:199], v182 offset:37888
	ds_read_b128 v[202:205], v182 offset:38912
	ds_read_b128 v[206:209], v182 offset:39936
	global_load_lds_dwordx4 v[224:225], off
	v_lshl_add_u64 v[224:225], s[68:69], 0, v[144:145]
	s_mov_b32 m0, s79
	s_nop 0
	global_load_lds_dwordx4 v[224:225], off
	s_waitcnt vmcnt(8)
	s_waitcnt lgkmcnt(0)
	s_setprio 1
	s_barrier
	v_mfma_f32_16x16x32_bf16 v[124:127], v[128:131], v[172:175], v[124:127]
	v_mfma_f32_16x16x32_bf16 v[120:123], v[136:139], v[172:175], v[120:123]
	v_mfma_f32_16x16x32_bf16 v[116:119], v[128:131], v[184:187], v[116:119]
	v_mfma_f32_16x16x32_bf16 v[112:115], v[136:139], v[184:187], v[112:115]
	v_mfma_f32_16x16x32_bf16 v[108:111], v[128:131], v[192:195], v[108:111]
	v_mfma_f32_16x16x32_bf16 v[104:107], v[136:139], v[192:195], v[104:107]
	v_mfma_f32_16x16x32_bf16 v[100:103], v[128:131], v[202:205], v[100:103]
	v_mfma_f32_16x16x32_bf16 v[96:99], v[136:139], v[202:205], v[96:99]
	v_mfma_f32_16x16x32_bf16 v[124:127], v[132:135], v[176:179], v[124:127]
	v_mfma_f32_16x16x32_bf16 v[120:123], v[152:155], v[176:179], v[120:123]
	v_mfma_f32_16x16x32_bf16 v[116:119], v[132:135], v[188:191], v[116:119]
	v_mfma_f32_16x16x32_bf16 v[112:115], v[152:155], v[188:191], v[112:115]
	v_mfma_f32_16x16x32_bf16 v[108:111], v[132:135], v[196:199], v[108:111]
	v_mfma_f32_16x16x32_bf16 v[104:107], v[152:155], v[196:199], v[104:107]
	v_mfma_f32_16x16x32_bf16 v[100:103], v[132:135], v[206:209], v[100:103]
	v_mfma_f32_16x16x32_bf16 v[96:99], v[152:155], v[206:209], v[96:99]
	s_setprio 0
	s_setprio 1
	v_mfma_f32_16x16x32_bf16 v[92:95], v[156:159], v[172:175], v[92:95]
	v_mfma_f32_16x16x32_bf16 v[88:91], v[164:167], v[172:175], v[88:91]
	v_mfma_f32_16x16x32_bf16 v[84:87], v[156:159], v[184:187], v[84:87]
	v_mfma_f32_16x16x32_bf16 v[80:83], v[164:167], v[184:187], v[80:83]
	v_mfma_f32_16x16x32_bf16 v[76:79], v[156:159], v[192:195], v[76:79]
	v_mfma_f32_16x16x32_bf16 v[72:75], v[164:167], v[192:195], v[72:75]
	v_mfma_f32_16x16x32_bf16 v[68:71], v[156:159], v[202:205], v[68:71]
	v_mfma_f32_16x16x32_bf16 v[64:67], v[164:167], v[202:205], v[64:67]
	v_mfma_f32_16x16x32_bf16 v[92:95], v[160:163], v[176:179], v[92:95]
	v_mfma_f32_16x16x32_bf16 v[88:91], v[168:171], v[176:179], v[88:91]
	v_mfma_f32_16x16x32_bf16 v[84:87], v[160:163], v[188:191], v[84:87]
	v_mfma_f32_16x16x32_bf16 v[80:83], v[168:171], v[188:191], v[80:83]
	v_mfma_f32_16x16x32_bf16 v[76:79], v[160:163], v[196:199], v[76:79]
	v_mfma_f32_16x16x32_bf16 v[72:75], v[168:171], v[196:199], v[72:75]
	v_mfma_f32_16x16x32_bf16 v[68:71], v[160:163], v[206:209], v[68:71]
	v_mfma_f32_16x16x32_bf16 v[64:67], v[168:171], v[206:209], v[64:67]
	s_barrier
	s_setprio 0
	s_add_i32 s68, s89, s72
	v_lshl_add_u64 v[212:213], v[212:213], 0, s[64:65]
	s_mov_b32 m0, s68
	ds_read_b128 v[172:175], v182 offset:49152
	ds_read_b128 v[176:179], v182 offset:50176
	ds_read_b128 v[184:187], v182 offset:51200
	ds_read_b128 v[188:191], v182 offset:52224
	ds_read_b128 v[192:195], v182 offset:53248
	ds_read_b128 v[196:199], v182 offset:54272
	ds_read_b128 v[202:205], v182 offset:55296
	ds_read_b128 v[206:209], v182 offset:56320
	global_load_lds_dwordx4 v[212:213], off
	v_lshl_add_u64 v[212:213], v[214:215], 0, s[64:65]
	s_add_i32 m0, s68, 0x2000
	s_add_i32 s68, s90, s72
	global_load_lds_dwordx4 v[212:213], off
	v_lshl_add_u64 v[212:213], v[216:217], 0, s[64:65]
	s_mov_b32 m0, s68
	s_nop 0
	global_load_lds_dwordx4 v[212:213], off
	v_lshl_add_u64 v[212:213], v[218:219], 0, s[64:65]
	s_add_i32 m0, s68, 0x2000
	s_nop 0
	global_load_lds_dwordx4 v[212:213], off
	v_lshl_add_u64 v[212:213], v[220:221], 0, s[64:65]
	s_mov_b32 m0, s82
	s_nop 0
	global_load_lds_dwordx4 v[212:213], off
	v_lshl_add_u64 v[212:213], v[222:223], 0, s[64:65]
	s_mov_b32 m0, s83
	s_nop 0
	global_load_lds_dwordx4 v[212:213], off
	s_waitcnt vmcnt(8)
	s_waitcnt lgkmcnt(0)
	s_setprio 1
	s_barrier
	v_mfma_f32_16x16x32_bf16 v[60:63], v[128:131], v[172:175], v[60:63]
	v_mfma_f32_16x16x32_bf16 v[56:59], v[136:139], v[172:175], v[56:59]
	v_mfma_f32_16x16x32_bf16 v[52:55], v[128:131], v[184:187], v[52:55]
	v_mfma_f32_16x16x32_bf16 v[48:51], v[136:139], v[184:187], v[48:51]
	v_mfma_f32_16x16x32_bf16 v[44:47], v[128:131], v[192:195], v[44:47]
	v_mfma_f32_16x16x32_bf16 v[40:43], v[136:139], v[192:195], v[40:43]
	v_mfma_f32_16x16x32_bf16 v[36:39], v[128:131], v[202:205], v[36:39]
	v_mfma_f32_16x16x32_bf16 v[32:35], v[136:139], v[202:205], v[32:35]
	v_mfma_f32_16x16x32_bf16 v[60:63], v[132:135], v[176:179], v[60:63]
	v_mfma_f32_16x16x32_bf16 v[56:59], v[152:155], v[176:179], v[56:59]
	v_mfma_f32_16x16x32_bf16 v[52:55], v[132:135], v[188:191], v[52:55]
	v_mfma_f32_16x16x32_bf16 v[48:51], v[152:155], v[188:191], v[48:51]
	v_mfma_f32_16x16x32_bf16 v[44:47], v[132:135], v[196:199], v[44:47]
	v_mfma_f32_16x16x32_bf16 v[40:43], v[152:155], v[196:199], v[40:43]
	v_mfma_f32_16x16x32_bf16 v[36:39], v[132:135], v[206:209], v[36:39]
	v_mfma_f32_16x16x32_bf16 v[32:35], v[152:155], v[206:209], v[32:35]
	s_setprio 0
	s_setprio 1
	v_mfma_f32_16x16x32_bf16 v[28:31], v[156:159], v[172:175], v[28:31]
	v_mfma_f32_16x16x32_bf16 v[24:27], v[164:167], v[172:175], v[24:27]
	v_mfma_f32_16x16x32_bf16 v[20:23], v[156:159], v[184:187], v[20:23]
	v_mfma_f32_16x16x32_bf16 v[16:19], v[164:167], v[184:187], v[16:19]
	v_mfma_f32_16x16x32_bf16 v[12:15], v[156:159], v[192:195], v[12:15]
	v_mfma_f32_16x16x32_bf16 v[8:11], v[164:167], v[192:195], v[8:11]
	v_mfma_f32_16x16x32_bf16 v[4:7], v[156:159], v[202:205], v[4:7]
	v_mfma_f32_16x16x32_bf16 v[0:3], v[164:167], v[202:205], v[0:3]
	v_mfma_f32_16x16x32_bf16 v[28:31], v[160:163], v[176:179], v[28:31]
	v_mfma_f32_16x16x32_bf16 v[24:27], v[168:171], v[176:179], v[24:27]
	v_mfma_f32_16x16x32_bf16 v[20:23], v[160:163], v[188:191], v[20:23]
	v_mfma_f32_16x16x32_bf16 v[16:19], v[168:171], v[188:191], v[16:19]
	v_mfma_f32_16x16x32_bf16 v[12:15], v[160:163], v[196:199], v[12:15]
	v_mfma_f32_16x16x32_bf16 v[8:11], v[168:171], v[196:199], v[8:11]
	v_mfma_f32_16x16x32_bf16 v[4:7], v[160:163], v[206:209], v[4:7]
	v_mfma_f32_16x16x32_bf16 v[0:3], v[168:171], v[206:209], v[0:3]
	s_barrier
	s_setprio 0
	s_add_u32 s4, s4, 0x100
	s_addc_u32 s5, s5, 0
	s_add_u32 s70, s70, 0x100
	s_addc_u32 s71, s71, 0
	s_cmp_ge_u32 s88, s80
	s_mov_b32 s68, s88
	s_cbranch_scc0 .LBB0_974
	s_and_b64 vcc, exec, s[18:19]
	s_cbranch_vccz .LBB0_977
	s_barrier

.LBB0_1102:
	s_add_u32 s34, s4, 0xfff80080
	s_addc_u32 s35, s5, -1
	s_add_i32 s68, 0, 0x10000
	s_cmp_eq_u32 s67, 28
	s_cselect_b32 s37, s25, s35
	s_cselect_b32 s36, s61, s34
	s_cselect_b32 s35, s23, s66
	s_cselect_b32 s34, s62, s63
	s_add_i32 s70, 0, 0x14000
	v_add_u32_e32 v84, s68, v173
	v_add_u32_e32 v108, s70, v173
	ds_read_b128 v[72:75], v84
	ds_read_b128 v[76:79], v84 offset:1024
	ds_read_b128 v[80:83], v84 offset:2048
	ds_read_b128 v[84:87], v84 offset:3072
	ds_read_b128 v[96:99], v108
	ds_read_b128 v[100:103], v108 offset:1024
	ds_read_b128 v[104:107], v108 offset:2048
	ds_read_b128 v[108:111], v108 offset:3072
	v_lshl_add_u64 v[170:171], s[4:5], 0, v[166:167]
	s_add_i32 m0, s31, 0xc000
	ds_read_b128 v[176:179], v174
	ds_read_b128 v[180:183], v174 offset:1024
	ds_read_b128 v[184:187], v174 offset:2048
	ds_read_b128 v[188:191], v174 offset:3072
	ds_read_b128 v[192:195], v174 offset:4096
	ds_read_b128 v[196:199], v174 offset:5120
	ds_read_b128 v[202:205], v174 offset:6144
	ds_read_b128 v[206:209], v174 offset:7168
	global_load_lds_dwordx4 v[170:171], off
	v_lshl_add_u64 v[170:171], s[4:5], 0, v[168:169]
	s_add_i32 m0, s31, 0xe000
	s_nop 0
	global_load_lds_dwordx4 v[170:171], off
	s_add_u32 vcc_lo, s4, 0xfff80000
	s_addc_u32 vcc_hi, s5, -1
	s_mov_b32 m0, s55
	s_nop 0
	global_load_lds_dwordx4 v164, vcc
	s_mov_b32 m0, s56
	s_nop 0
	global_load_lds_dwordx4 v162, vcc
	s_waitcnt vmcnt(4)
	s_waitcnt lgkmcnt(0)
	s_setprio 1
	s_barrier
	v_mfma_f32_16x16x32_bf16 v[156:159], v[72:75], v[176:179], v[156:159]
	v_mfma_f32_16x16x32_bf16 v[152:155], v[80:83], v[176:179], v[152:155]
	v_mfma_f32_16x16x32_bf16 v[140:143], v[72:75], v[184:187], v[140:143]
	v_mfma_f32_16x16x32_bf16 v[132:135], v[80:83], v[184:187], v[132:135]
	v_mfma_f32_16x16x32_bf16 v[124:127], v[72:75], v[192:195], v[124:127]
	v_mfma_f32_16x16x32_bf16 v[116:119], v[80:83], v[192:195], v[116:119]
	v_mfma_f32_16x16x32_bf16 v[92:95], v[72:75], v[202:205], v[92:95]
	v_mfma_f32_16x16x32_bf16 v[68:71], v[80:83], v[202:205], v[68:71]
	v_mfma_f32_16x16x32_bf16 v[156:159], v[76:79], v[180:183], v[156:159]
	v_mfma_f32_16x16x32_bf16 v[152:155], v[84:87], v[180:183], v[152:155]
	v_mfma_f32_16x16x32_bf16 v[140:143], v[76:79], v[188:191], v[140:143]
	v_mfma_f32_16x16x32_bf16 v[132:135], v[84:87], v[188:191], v[132:135]
	v_mfma_f32_16x16x32_bf16 v[124:127], v[76:79], v[196:199], v[124:127]
	v_mfma_f32_16x16x32_bf16 v[116:119], v[84:87], v[196:199], v[116:119]
	v_mfma_f32_16x16x32_bf16 v[92:95], v[76:79], v[206:209], v[92:95]
	v_mfma_f32_16x16x32_bf16 v[68:71], v[84:87], v[206:209], v[68:71]
	s_setprio 0
	s_setprio 1
	v_mfma_f32_16x16x32_bf16 v[148:151], v[96:99], v[176:179], v[148:151]
	v_mfma_f32_16x16x32_bf16 v[144:147], v[104:107], v[176:179], v[144:147]
	v_mfma_f32_16x16x32_bf16 v[136:139], v[96:99], v[184:187], v[136:139]
	v_mfma_f32_16x16x32_bf16 v[128:131], v[104:107], v[184:187], v[128:131]
	v_mfma_f32_16x16x32_bf16 v[120:123], v[96:99], v[192:195], v[120:123]
	v_mfma_f32_16x16x32_bf16 v[112:115], v[104:107], v[192:195], v[112:115]
	v_mfma_f32_16x16x32_bf16 v[88:91], v[96:99], v[202:205], v[88:91]
	v_mfma_f32_16x16x32_bf16 v[64:67], v[104:107], v[202:205], v[64:67]
	v_mfma_f32_16x16x32_bf16 v[148:151], v[100:103], v[180:183], v[148:151]
	v_mfma_f32_16x16x32_bf16 v[144:147], v[108:111], v[180:183], v[144:147]
	v_mfma_f32_16x16x32_bf16 v[136:139], v[100:103], v[188:191], v[136:139]
	v_mfma_f32_16x16x32_bf16 v[128:131], v[108:111], v[188:191], v[128:131]
	v_mfma_f32_16x16x32_bf16 v[120:123], v[100:103], v[196:199], v[120:123]
	v_mfma_f32_16x16x32_bf16 v[112:115], v[108:111], v[196:199], v[112:115]
	v_mfma_f32_16x16x32_bf16 v[88:91], v[100:103], v[206:209], v[88:91]
	v_mfma_f32_16x16x32_bf16 v[64:67], v[108:111], v[206:209], v[64:67]
	s_barrier
	s_setprio 0
	s_add_i32 s68, s68, s53
	v_lshl_add_u64 v[170:171], s[34:35], 0, v[200:201]
	s_mov_b32 m0, s68
	ds_read_b128 v[176:179], v174 offset:16384
	ds_read_b128 v[180:183], v174 offset:17408
	ds_read_b128 v[184:187], v174 offset:18432
	ds_read_b128 v[188:191], v174 offset:19456
	ds_read_b128 v[192:195], v174 offset:20480
	ds_read_b128 v[196:199], v174 offset:21504
	ds_read_b128 v[202:205], v174 offset:22528
	ds_read_b128 v[206:209], v174 offset:23552
	global_load_lds_dwordx4 v[170:171], off
	s_add_i32 m0, s68, 0x2000
	s_add_u32 s68, s34, 0x80000
	v_lshl_add_u64 v[212:213], s[34:35], 0, v[160:161]
	s_addc_u32 s69, s35, 0
	s_add_i32 s70, s70, s53
	global_load_lds_dwordx4 v[212:213], off
	v_lshl_add_u64 v[214:215], s[68:69], 0, v[200:201]
	s_mov_b32 m0, s70
	global_load_lds_dwordx4 v[214:215], off
	v_lshl_add_u64 v[214:215], s[68:69], 0, v[160:161]
	s_add_i32 m0, s70, 0x2000
	s_nop 0
	global_load_lds_dwordx4 v[214:215], off
	s_waitcnt vmcnt(4)
	s_waitcnt lgkmcnt(0)
	s_setprio 1
	s_barrier
	v_mfma_f32_16x16x32_bf16 v[60:63], v[72:75], v[176:179], v[60:63]
	v_mfma_f32_16x16x32_bf16 v[52:55], v[80:83], v[176:179], v[52:55]
	v_mfma_f32_16x16x32_bf16 v[44:47], v[72:75], v[184:187], v[44:47]
	v_mfma_f32_16x16x32_bf16 v[36:39], v[80:83], v[184:187], v[36:39]
	v_mfma_f32_16x16x32_bf16 v[28:31], v[72:75], v[192:195], v[28:31]
	v_mfma_f32_16x16x32_bf16 v[20:23], v[80:83], v[192:195], v[20:23]
	v_mfma_f32_16x16x32_bf16 v[12:15], v[72:75], v[202:205], v[12:15]
	v_mfma_f32_16x16x32_bf16 v[4:7], v[80:83], v[202:205], v[4:7]
	v_mfma_f32_16x16x32_bf16 v[60:63], v[76:79], v[180:183], v[60:63]
	v_mfma_f32_16x16x32_bf16 v[52:55], v[84:87], v[180:183], v[52:55]
	v_mfma_f32_16x16x32_bf16 v[44:47], v[76:79], v[188:191], v[44:47]
	v_mfma_f32_16x16x32_bf16 v[36:39], v[84:87], v[188:191], v[36:39]
	v_mfma_f32_16x16x32_bf16 v[28:31], v[76:79], v[196:199], v[28:31]
	v_mfma_f32_16x16x32_bf16 v[20:23], v[84:87], v[196:199], v[20:23]
	v_mfma_f32_16x16x32_bf16 v[12:15], v[76:79], v[206:209], v[12:15]
	v_mfma_f32_16x16x32_bf16 v[4:7], v[84:87], v[206:209], v[4:7]
	s_setprio 0
	s_setprio 1
	v_mfma_f32_16x16x32_bf16 v[56:59], v[96:99], v[176:179], v[56:59]
	v_mfma_f32_16x16x32_bf16 v[48:51], v[104:107], v[176:179], v[48:51]
	v_mfma_f32_16x16x32_bf16 v[40:43], v[96:99], v[184:187], v[40:43]
	v_mfma_f32_16x16x32_bf16 v[32:35], v[104:107], v[184:187], v[32:35]
	v_mfma_f32_16x16x32_bf16 v[24:27], v[96:99], v[192:195], v[24:27]
	v_mfma_f32_16x16x32_bf16 v[16:19], v[104:107], v[192:195], v[16:19]
	v_mfma_f32_16x16x32_bf16 v[8:11], v[96:99], v[202:205], v[8:11]
	v_mfma_f32_16x16x32_bf16 v[0:3], v[104:107], v[202:205], v[0:3]
	v_mfma_f32_16x16x32_bf16 v[56:59], v[100:103], v[180:183], v[56:59]
	v_mfma_f32_16x16x32_bf16 v[48:51], v[108:111], v[180:183], v[48:51]
	v_mfma_f32_16x16x32_bf16 v[40:43], v[100:103], v[188:191], v[40:43]
	v_mfma_f32_16x16x32_bf16 v[32:35], v[108:111], v[188:191], v[32:35]
	v_mfma_f32_16x16x32_bf16 v[24:27], v[100:103], v[196:199], v[24:27]
	v_mfma_f32_16x16x32_bf16 v[16:19], v[108:111], v[196:199], v[16:19]
	v_mfma_f32_16x16x32_bf16 v[8:11], v[100:103], v[206:209], v[8:11]
	v_mfma_f32_16x16x32_bf16 v[0:3], v[108:111], v[206:209], v[0:3]
	s_barrier
	s_setprio 0
	s_add_i32 s68, 0, 0x18000
	s_add_i32 s69, 0, 0x1c000
	v_add_u32_e32 v84, s68, v173
	v_add_u32_e32 v108, s69, v173
	ds_read_b128 v[72:75], v84
	ds_read_b128 v[76:79], v84 offset:1024
	ds_read_b128 v[80:83], v84 offset:2048
	ds_read_b128 v[84:87], v84 offset:3072
	ds_read_b128 v[96:99], v108
	ds_read_b128 v[100:103], v108 offset:1024
	ds_read_b128 v[104:107], v108 offset:2048
	ds_read_b128 v[108:111], v108 offset:3072
	s_mov_b32 m0, s31
	s_nop 0
	global_load_lds_dwordx4 v164, s[36:37]
	s_mov_b32 m0, s42
	s_nop 0
	global_load_lds_dwordx4 v162, s[36:37]
	s_add_u32 s36, s36, 0x80000
	s_addc_u32 s37, s37, 0
	s_mov_b32 m0, s43
	v_lshl_add_u64 v[218:219], s[36:37], 0, v[164:165]
	ds_read_b128 v[176:179], v174 offset:32768
	ds_read_b128 v[180:183], v174 offset:33792
	ds_read_b128 v[184:187], v174 offset:34816
	ds_read_b128 v[188:191], v174 offset:35840
	ds_read_b128 v[192:195], v174 offset:36864
	ds_read_b128 v[196:199], v174 offset:37888
	ds_read_b128 v[202:205], v174 offset:38912
	ds_read_b128 v[206:209], v174 offset:39936
	global_load_lds_dwordx4 v[218:219], off
	v_lshl_add_u64 v[218:219], s[36:37], 0, v[162:163]
	s_mov_b32 m0, s54
	s_nop 0
	global_load_lds_dwordx4 v[218:219], off
	s_waitcnt vmcnt(4)
	s_waitcnt lgkmcnt(0)
	s_setprio 1
	s_barrier
	v_mfma_f32_16x16x32_bf16 v[156:159], v[72:75], v[176:179], v[156:159]
	v_mfma_f32_16x16x32_bf16 v[152:155], v[80:83], v[176:179], v[152:155]
	v_mfma_f32_16x16x32_bf16 v[140:143], v[72:75], v[184:187], v[140:143]
	v_mfma_f32_16x16x32_bf16 v[132:135], v[80:83], v[184:187], v[132:135]
	v_mfma_f32_16x16x32_bf16 v[124:127], v[72:75], v[192:195], v[124:127]
	v_mfma_f32_16x16x32_bf16 v[116:119], v[80:83], v[192:195], v[116:119]
	v_mfma_f32_16x16x32_bf16 v[92:95], v[72:75], v[202:205], v[92:95]
	v_mfma_f32_16x16x32_bf16 v[68:71], v[80:83], v[202:205], v[68:71]
	v_mfma_f32_16x16x32_bf16 v[156:159], v[76:79], v[180:183], v[156:159]
	v_mfma_f32_16x16x32_bf16 v[152:155], v[84:87], v[180:183], v[152:155]
	v_mfma_f32_16x16x32_bf16 v[140:143], v[76:79], v[188:191], v[140:143]
	v_mfma_f32_16x16x32_bf16 v[132:135], v[84:87], v[188:191], v[132:135]
	v_mfma_f32_16x16x32_bf16 v[124:127], v[76:79], v[196:199], v[124:127]
	v_mfma_f32_16x16x32_bf16 v[116:119], v[84:87], v[196:199], v[116:119]
	v_mfma_f32_16x16x32_bf16 v[92:95], v[76:79], v[206:209], v[92:95]
	v_mfma_f32_16x16x32_bf16 v[68:71], v[84:87], v[206:209], v[68:71]
	s_setprio 0
	s_setprio 1
	v_mfma_f32_16x16x32_bf16 v[148:151], v[96:99], v[176:179], v[148:151]
	v_mfma_f32_16x16x32_bf16 v[144:147], v[104:107], v[176:179], v[144:147]
	v_mfma_f32_16x16x32_bf16 v[136:139], v[96:99], v[184:187], v[136:139]
	v_mfma_f32_16x16x32_bf16 v[128:131], v[104:107], v[184:187], v[128:131]
	v_mfma_f32_16x16x32_bf16 v[120:123], v[96:99], v[192:195], v[120:123]
	v_mfma_f32_16x16x32_bf16 v[112:115], v[104:107], v[192:195], v[112:115]
	v_mfma_f32_16x16x32_bf16 v[88:91], v[96:99], v[202:205], v[88:91]
	v_mfma_f32_16x16x32_bf16 v[64:67], v[104:107], v[202:205], v[64:67]
	v_mfma_f32_16x16x32_bf16 v[148:151], v[100:103], v[180:183], v[148:151]
	v_mfma_f32_16x16x32_bf16 v[144:147], v[108:111], v[180:183], v[144:147]
	v_mfma_f32_16x16x32_bf16 v[136:139], v[100:103], v[188:191], v[136:139]
	v_mfma_f32_16x16x32_bf16 v[128:131], v[108:111], v[188:191], v[128:131]
	v_mfma_f32_16x16x32_bf16 v[120:123], v[100:103], v[196:199], v[120:123]
	v_mfma_f32_16x16x32_bf16 v[112:115], v[108:111], v[196:199], v[112:115]
	v_mfma_f32_16x16x32_bf16 v[88:91], v[100:103], v[206:209], v[88:91]
	v_mfma_f32_16x16x32_bf16 v[64:67], v[108:111], v[206:209], v[64:67]
	s_barrier
	s_setprio 0
	s_add_i32 s36, s68, s53
	v_lshl_add_u64 v[170:171], v[170:171], 0, s[64:65]
	s_mov_b32 m0, s36
	ds_read_b128 v[176:179], v174 offset:49152
	ds_read_b128 v[180:183], v174 offset:50176
	ds_read_b128 v[184:187], v174 offset:51200
	ds_read_b128 v[188:191], v174 offset:52224
	ds_read_b128 v[192:195], v174 offset:53248
	ds_read_b128 v[196:199], v174 offset:54272
	ds_read_b128 v[202:205], v174 offset:55296
	ds_read_b128 v[206:209], v174 offset:56320
	global_load_lds_dwordx4 v[170:171], off
	s_add_i32 m0, s36, 0x2000
	s_add_u32 s34, s34, 0x80080
	v_lshl_add_u64 v[170:171], v[212:213], 0, s[64:65]
	s_addc_u32 s35, s35, 0
	s_add_i32 s36, s69, s53
	global_load_lds_dwordx4 v[170:171], off
	v_lshl_add_u64 v[170:171], s[34:35], 0, v[200:201]
	s_mov_b32 m0, s36
	s_nop 0
	global_load_lds_dwordx4 v[170:171], off
	v_lshl_add_u64 v[170:171], s[34:35], 0, v[160:161]
	s_add_i32 m0, s36, 0x2000
	s_nop 0
	global_load_lds_dwordx4 v[170:171], off
	s_waitcnt vmcnt(4)
	s_waitcnt lgkmcnt(0)
	s_setprio 1
	s_barrier
	v_mfma_f32_16x16x32_bf16 v[60:63], v[72:75], v[176:179], v[60:63]
	v_mfma_f32_16x16x32_bf16 v[52:55], v[80:83], v[176:179], v[52:55]
	v_mfma_f32_16x16x32_bf16 v[44:47], v[72:75], v[184:187], v[44:47]
	v_mfma_f32_16x16x32_bf16 v[36:39], v[80:83], v[184:187], v[36:39]
	v_mfma_f32_16x16x32_bf16 v[28:31], v[72:75], v[192:195], v[28:31]
	v_mfma_f32_16x16x32_bf16 v[20:23], v[80:83], v[192:195], v[20:23]
	v_mfma_f32_16x16x32_bf16 v[12:15], v[72:75], v[202:205], v[12:15]
	v_mfma_f32_16x16x32_bf16 v[4:7], v[80:83], v[202:205], v[4:7]
	v_mfma_f32_16x16x32_bf16 v[60:63], v[76:79], v[180:183], v[60:63]
	v_mfma_f32_16x16x32_bf16 v[52:55], v[84:87], v[180:183], v[52:55]
	v_mfma_f32_16x16x32_bf16 v[44:47], v[76:79], v[188:191], v[44:47]
	v_mfma_f32_16x16x32_bf16 v[36:39], v[84:87], v[188:191], v[36:39]
	v_mfma_f32_16x16x32_bf16 v[28:31], v[76:79], v[196:199], v[28:31]
	v_mfma_f32_16x16x32_bf16 v[20:23], v[84:87], v[196:199], v[20:23]
	v_mfma_f32_16x16x32_bf16 v[12:15], v[76:79], v[206:209], v[12:15]
	v_mfma_f32_16x16x32_bf16 v[4:7], v[84:87], v[206:209], v[4:7]
	s_setprio 0
	s_setprio 1
	v_mfma_f32_16x16x32_bf16 v[56:59], v[96:99], v[176:179], v[56:59]
	v_mfma_f32_16x16x32_bf16 v[48:51], v[104:107], v[176:179], v[48:51]
	v_mfma_f32_16x16x32_bf16 v[40:43], v[96:99], v[184:187], v[40:43]
	v_mfma_f32_16x16x32_bf16 v[32:35], v[104:107], v[184:187], v[32:35]
	v_mfma_f32_16x16x32_bf16 v[24:27], v[96:99], v[192:195], v[24:27]
	v_mfma_f32_16x16x32_bf16 v[16:19], v[104:107], v[192:195], v[16:19]
	v_mfma_f32_16x16x32_bf16 v[8:11], v[96:99], v[202:205], v[8:11]
	v_mfma_f32_16x16x32_bf16 v[0:3], v[104:107], v[202:205], v[0:3]
	v_mfma_f32_16x16x32_bf16 v[56:59], v[100:103], v[180:183], v[56:59]
	v_mfma_f32_16x16x32_bf16 v[48:51], v[108:111], v[180:183], v[48:51]
	v_mfma_f32_16x16x32_bf16 v[40:43], v[100:103], v[188:191], v[40:43]
	v_mfma_f32_16x16x32_bf16 v[32:35], v[108:111], v[188:191], v[32:35]
	v_mfma_f32_16x16x32_bf16 v[24:27], v[100:103], v[196:199], v[24:27]
	v_mfma_f32_16x16x32_bf16 v[16:19], v[108:111], v[196:199], v[16:19]
	v_mfma_f32_16x16x32_bf16 v[8:11], v[100:103], v[206:209], v[8:11]
	v_mfma_f32_16x16x32_bf16 v[0:3], v[108:111], v[206:209], v[0:3]
	s_barrier
	s_setprio 0
	s_add_i32 s67, s67, 2
	s_add_u32 s4, s4, 0x100
	s_addc_u32 s5, s5, 0
	s_add_u32 s63, s63, 0x100
	s_addc_u32 s66, s66, 0
	s_cmp_gt_u32 s67, 29
	s_cbranch_scc0 .LBB0_1102
	s_and_b64 vcc, exec, s[20:21]
	s_cbranch_vccz .LBB0_1105
	s_barrier

.LBB0_1149:
	s_add_i32 s51, s22, 2
	s_add_u32 s53, s20, 0x80
	s_addc_u32 s23, s21, 0
	s_add_i32 s56, 0, 0x10000
	s_cmp_eq_u32 s40, s22
	s_cselect_b32 s23, s5, s23
	s_cselect_b32 s22, s4, s53
	v_add_u32_e32 v141, s56, v139
	s_cselect_b32 s55, s19, s50
	s_cselect_b32 s54, s18, s49
	s_add_i32 s53, 0, 0x14000
	ds_read_b128 v[142:145], v141
	ds_read_b128 v[146:149], v141 offset:1024
	ds_read_b128 v[150:153], v141 offset:2048
	ds_read_b128 v[154:157], v141 offset:3072
	v_add_u32_e32 v141, s53, v139
	ds_read_b128 v[158:161], v141
	ds_read_b128 v[162:165], v141 offset:1024
	ds_read_b128 v[166:169], v141 offset:2048
	ds_read_b128 v[170:173], v141 offset:3072
	v_lshl_add_u64 v[198:199], s[20:21], 0, v[134:135]
	s_add_i32 m0, s29, 0xc000
	ds_read_b128 v[174:177], v140
	ds_read_b128 v[178:181], v140 offset:1024
	ds_read_b128 v[182:185], v140 offset:2048
	ds_read_b128 v[186:189], v140 offset:3072
	ds_read_b128 v[190:193], v140 offset:4096
	ds_read_b128 v[194:197], v140 offset:5120
	ds_read_b128 v[202:205], v140 offset:6144
	ds_read_b128 v[206:209], v140 offset:7168
	global_load_lds_dwordx4 v[198:199], off
	v_lshl_add_u64 v[198:199], s[20:21], 0, v[136:137]
	s_add_i32 m0, s29, 0xe000
	s_nop 0
	global_load_lds_dwordx4 v[198:199], off
	s_waitcnt vmcnt(8)
	s_waitcnt lgkmcnt(0)
	s_setprio 1
	s_barrier
	v_mfma_f32_16x16x32_bf16 v[124:127], v[142:145], v[174:177], v[124:127]
	v_mfma_f32_16x16x32_bf16 v[120:123], v[150:153], v[174:177], v[120:123]
	v_mfma_f32_16x16x32_bf16 v[108:111], v[142:145], v[182:185], v[108:111]
	v_mfma_f32_16x16x32_bf16 v[104:107], v[150:153], v[182:185], v[104:107]
	v_mfma_f32_16x16x32_bf16 v[92:95], v[142:145], v[190:193], v[92:95]
	v_mfma_f32_16x16x32_bf16 v[88:91], v[150:153], v[190:193], v[88:91]
	v_mfma_f32_16x16x32_bf16 v[76:79], v[142:145], v[202:205], v[76:79]
	v_mfma_f32_16x16x32_bf16 v[72:75], v[150:153], v[202:205], v[72:75]
	v_mfma_f32_16x16x32_bf16 v[124:127], v[146:149], v[178:181], v[124:127]
	v_mfma_f32_16x16x32_bf16 v[120:123], v[154:157], v[178:181], v[120:123]
	v_mfma_f32_16x16x32_bf16 v[108:111], v[146:149], v[186:189], v[108:111]
	v_mfma_f32_16x16x32_bf16 v[104:107], v[154:157], v[186:189], v[104:107]
	v_mfma_f32_16x16x32_bf16 v[92:95], v[146:149], v[194:197], v[92:95]
	v_mfma_f32_16x16x32_bf16 v[88:91], v[154:157], v[194:197], v[88:91]
	v_mfma_f32_16x16x32_bf16 v[76:79], v[146:149], v[206:209], v[76:79]
	v_mfma_f32_16x16x32_bf16 v[72:75], v[154:157], v[206:209], v[72:75]
	s_setprio 0
	s_setprio 1
	v_mfma_f32_16x16x32_bf16 v[116:119], v[158:161], v[174:177], v[116:119]
	v_mfma_f32_16x16x32_bf16 v[112:115], v[166:169], v[174:177], v[112:115]
	v_mfma_f32_16x16x32_bf16 v[100:103], v[158:161], v[182:185], v[100:103]
	v_mfma_f32_16x16x32_bf16 v[96:99], v[166:169], v[182:185], v[96:99]
	v_mfma_f32_16x16x32_bf16 v[84:87], v[158:161], v[190:193], v[84:87]
	v_mfma_f32_16x16x32_bf16 v[80:83], v[166:169], v[190:193], v[80:83]
	v_mfma_f32_16x16x32_bf16 v[68:71], v[158:161], v[202:205], v[68:71]
	v_mfma_f32_16x16x32_bf16 v[64:67], v[166:169], v[202:205], v[64:67]
	v_mfma_f32_16x16x32_bf16 v[116:119], v[162:165], v[178:181], v[116:119]
	v_mfma_f32_16x16x32_bf16 v[112:115], v[170:173], v[178:181], v[112:115]
	v_mfma_f32_16x16x32_bf16 v[100:103], v[162:165], v[186:189], v[100:103]
	v_mfma_f32_16x16x32_bf16 v[96:99], v[170:173], v[186:189], v[96:99]
	v_mfma_f32_16x16x32_bf16 v[84:87], v[162:165], v[194:197], v[84:87]
	v_mfma_f32_16x16x32_bf16 v[80:83], v[170:173], v[194:197], v[80:83]
	v_mfma_f32_16x16x32_bf16 v[68:71], v[162:165], v[206:209], v[68:71]
	v_mfma_f32_16x16x32_bf16 v[64:67], v[170:173], v[206:209], v[64:67]
	s_barrier
	s_setprio 0
	s_add_i32 s56, s56, s28
	v_lshl_add_u64 v[198:199], s[54:55], 0, v[200:201]
	s_mov_b32 m0, s56
	ds_read_b128 v[174:177], v140 offset:16384
	ds_read_b128 v[178:181], v140 offset:17408
	ds_read_b128 v[182:185], v140 offset:18432
	ds_read_b128 v[186:189], v140 offset:19456
	ds_read_b128 v[190:193], v140 offset:20480
	ds_read_b128 v[194:197], v140 offset:21504
	ds_read_b128 v[202:205], v140 offset:22528
	ds_read_b128 v[206:209], v140 offset:23552
	global_load_lds_dwordx4 v[198:199], off
	s_add_i32 m0, s56, 0x2000
	v_lshl_add_u64 v[212:213], s[54:55], 0, v[128:129]
	s_add_u32 s54, s54, s8
	s_addc_u32 s55, s55, s9
	s_add_i32 s53, s53, s28
	global_load_lds_dwordx4 v[212:213], off
	v_lshl_add_u64 v[214:215], s[54:55], 0, v[200:201]
	s_mov_b32 m0, s53
	v_lshl_add_u64 v[216:217], s[54:55], 0, v[128:129]
	global_load_lds_dwordx4 v[214:215], off
	s_add_i32 m0, s53, 0x2000
	v_lshl_add_u64 v[218:219], s[22:23], 0, v[132:133]
	global_load_lds_dwordx4 v[216:217], off
	s_mov_b32 m0, s29
	v_lshl_add_u64 v[220:221], s[22:23], 0, v[130:131]
	global_load_lds_dwordx4 v[218:219], off
	s_mov_b32 m0, s30
	s_nop 0
	global_load_lds_dwordx4 v[220:221], off
	s_waitcnt vmcnt(8)
	s_waitcnt lgkmcnt(0)
	s_setprio 1
	s_barrier
	v_mfma_f32_16x16x32_bf16 v[60:63], v[142:145], v[174:177], v[60:63]
	v_mfma_f32_16x16x32_bf16 v[56:59], v[150:153], v[174:177], v[56:59]
	v_mfma_f32_16x16x32_bf16 v[44:47], v[142:145], v[182:185], v[44:47]
	v_mfma_f32_16x16x32_bf16 v[40:43], v[150:153], v[182:185], v[40:43]
	v_mfma_f32_16x16x32_bf16 v[28:31], v[142:145], v[190:193], v[28:31]
	v_mfma_f32_16x16x32_bf16 v[24:27], v[150:153], v[190:193], v[24:27]
	v_mfma_f32_16x16x32_bf16 v[12:15], v[142:145], v[202:205], v[12:15]
	v_mfma_f32_16x16x32_bf16 v[8:11], v[150:153], v[202:205], v[8:11]
	v_mfma_f32_16x16x32_bf16 v[60:63], v[146:149], v[178:181], v[60:63]
	v_mfma_f32_16x16x32_bf16 v[56:59], v[154:157], v[178:181], v[56:59]
	v_mfma_f32_16x16x32_bf16 v[44:47], v[146:149], v[186:189], v[44:47]
	v_mfma_f32_16x16x32_bf16 v[40:43], v[154:157], v[186:189], v[40:43]
	v_mfma_f32_16x16x32_bf16 v[28:31], v[146:149], v[194:197], v[28:31]
	v_mfma_f32_16x16x32_bf16 v[24:27], v[154:157], v[194:197], v[24:27]
	v_mfma_f32_16x16x32_bf16 v[12:15], v[146:149], v[206:209], v[12:15]
	v_mfma_f32_16x16x32_bf16 v[8:11], v[154:157], v[206:209], v[8:11]
	s_setprio 0
	s_setprio 1
	v_mfma_f32_16x16x32_bf16 v[52:55], v[158:161], v[174:177], v[52:55]
	v_mfma_f32_16x16x32_bf16 v[48:51], v[166:169], v[174:177], v[48:51]
	v_mfma_f32_16x16x32_bf16 v[36:39], v[158:161], v[182:185], v[36:39]
	v_mfma_f32_16x16x32_bf16 v[32:35], v[166:169], v[182:185], v[32:35]
	v_mfma_f32_16x16x32_bf16 v[20:23], v[158:161], v[190:193], v[20:23]
	v_mfma_f32_16x16x32_bf16 v[16:19], v[166:169], v[190:193], v[16:19]
	v_mfma_f32_16x16x32_bf16 v[4:7], v[158:161], v[202:205], v[4:7]
	v_mfma_f32_16x16x32_bf16 v[0:3], v[166:169], v[202:205], v[0:3]
	v_mfma_f32_16x16x32_bf16 v[52:55], v[162:165], v[178:181], v[52:55]
	v_mfma_f32_16x16x32_bf16 v[48:51], v[170:173], v[178:181], v[48:51]
	v_mfma_f32_16x16x32_bf16 v[36:39], v[162:165], v[186:189], v[36:39]
	v_mfma_f32_16x16x32_bf16 v[32:35], v[170:173], v[186:189], v[32:35]
	v_mfma_f32_16x16x32_bf16 v[20:23], v[162:165], v[194:197], v[20:23]
	v_mfma_f32_16x16x32_bf16 v[16:19], v[170:173], v[194:197], v[16:19]
	v_mfma_f32_16x16x32_bf16 v[4:7], v[162:165], v[206:209], v[4:7]
	v_mfma_f32_16x16x32_bf16 v[0:3], v[170:173], v[206:209], v[0:3]
	s_barrier
	s_setprio 0
	s_add_i32 s53, 0, 0x18000
	v_add_u32_e32 v141, s53, v139
	s_add_i32 s54, 0, 0x1c000
	ds_read_b128 v[142:145], v141
	ds_read_b128 v[146:149], v141 offset:1024
	ds_read_b128 v[150:153], v141 offset:2048
	ds_read_b128 v[154:157], v141 offset:3072
	v_add_u32_e32 v141, s54, v139
	ds_read_b128 v[158:161], v141
	ds_read_b128 v[162:165], v141 offset:1024
	ds_read_b128 v[166:169], v141 offset:2048
	ds_read_b128 v[170:173], v141 offset:3072
	s_add_u32 s22, s22, s8
	s_addc_u32 s23, s23, s9
	s_mov_b32 m0, s31
	v_lshl_add_u64 v[222:223], s[22:23], 0, v[132:133]
	ds_read_b128 v[174:177], v140 offset:32768
	ds_read_b128 v[178:181], v140 offset:33792
	ds_read_b128 v[182:185], v140 offset:34816
	ds_read_b128 v[186:189], v140 offset:35840
	ds_read_b128 v[190:193], v140 offset:36864
	ds_read_b128 v[194:197], v140 offset:37888
	ds_read_b128 v[202:205], v140 offset:38912
	ds_read_b128 v[206:209], v140 offset:39936
	global_load_lds_dwordx4 v[222:223], off
	v_lshl_add_u64 v[222:223], s[22:23], 0, v[130:131]
	s_mov_b32 m0, s33
	s_nop 0
	global_load_lds_dwordx4 v[222:223], off
	s_waitcnt vmcnt(8)
	s_waitcnt lgkmcnt(0)
	s_setprio 1
	s_barrier
	v_mfma_f32_16x16x32_bf16 v[124:127], v[142:145], v[174:177], v[124:127]
	v_mfma_f32_16x16x32_bf16 v[120:123], v[150:153], v[174:177], v[120:123]
	v_mfma_f32_16x16x32_bf16 v[108:111], v[142:145], v[182:185], v[108:111]
	v_mfma_f32_16x16x32_bf16 v[104:107], v[150:153], v[182:185], v[104:107]
	v_mfma_f32_16x16x32_bf16 v[92:95], v[142:145], v[190:193], v[92:95]
	v_mfma_f32_16x16x32_bf16 v[88:91], v[150:153], v[190:193], v[88:91]
	v_mfma_f32_16x16x32_bf16 v[76:79], v[142:145], v[202:205], v[76:79]
	v_mfma_f32_16x16x32_bf16 v[72:75], v[150:153], v[202:205], v[72:75]
	v_mfma_f32_16x16x32_bf16 v[124:127], v[146:149], v[178:181], v[124:127]
	v_mfma_f32_16x16x32_bf16 v[120:123], v[154:157], v[178:181], v[120:123]
	v_mfma_f32_16x16x32_bf16 v[108:111], v[146:149], v[186:189], v[108:111]
	v_mfma_f32_16x16x32_bf16 v[104:107], v[154:157], v[186:189], v[104:107]
	v_mfma_f32_16x16x32_bf16 v[92:95], v[146:149], v[194:197], v[92:95]
	v_mfma_f32_16x16x32_bf16 v[88:91], v[154:157], v[194:197], v[88:91]
	v_mfma_f32_16x16x32_bf16 v[76:79], v[146:149], v[206:209], v[76:79]
	v_mfma_f32_16x16x32_bf16 v[72:75], v[154:157], v[206:209], v[72:75]
	s_setprio 0
	s_setprio 1
	v_mfma_f32_16x16x32_bf16 v[116:119], v[158:161], v[174:177], v[116:119]
	v_mfma_f32_16x16x32_bf16 v[112:115], v[166:169], v[174:177], v[112:115]
	v_mfma_f32_16x16x32_bf16 v[100:103], v[158:161], v[182:185], v[100:103]
	v_mfma_f32_16x16x32_bf16 v[96:99], v[166:169], v[182:185], v[96:99]
	v_mfma_f32_16x16x32_bf16 v[84:87], v[158:161], v[190:193], v[84:87]
	v_mfma_f32_16x16x32_bf16 v[80:83], v[166:169], v[190:193], v[80:83]
	v_mfma_f32_16x16x32_bf16 v[68:71], v[158:161], v[202:205], v[68:71]
	v_mfma_f32_16x16x32_bf16 v[64:67], v[166:169], v[202:205], v[64:67]
	v_mfma_f32_16x16x32_bf16 v[116:119], v[162:165], v[178:181], v[116:119]
	v_mfma_f32_16x16x32_bf16 v[112:115], v[170:173], v[178:181], v[112:115]
	v_mfma_f32_16x16x32_bf16 v[100:103], v[162:165], v[186:189], v[100:103]
	v_mfma_f32_16x16x32_bf16 v[96:99], v[170:173], v[186:189], v[96:99]
	v_mfma_f32_16x16x32_bf16 v[84:87], v[162:165], v[194:197], v[84:87]
	v_mfma_f32_16x16x32_bf16 v[80:83], v[170:173], v[194:197], v[80:83]
	v_mfma_f32_16x16x32_bf16 v[68:71], v[162:165], v[206:209], v[68:71]
	v_mfma_f32_16x16x32_bf16 v[64:67], v[170:173], v[206:209], v[64:67]
	s_barrier
	s_setprio 0
	s_add_i32 s22, s53, s28
	v_lshl_add_u64 v[198:199], v[198:199], 0, s[64:65]
	s_mov_b32 m0, s22
	ds_read_b128 v[174:177], v140 offset:49152
	ds_read_b128 v[178:181], v140 offset:50176
	ds_read_b128 v[182:185], v140 offset:51200
	ds_read_b128 v[186:189], v140 offset:52224
	ds_read_b128 v[190:193], v140 offset:53248
	ds_read_b128 v[194:197], v140 offset:54272
	ds_read_b128 v[202:205], v140 offset:55296
	ds_read_b128 v[206:209], v140 offset:56320
	global_load_lds_dwordx4 v[198:199], off
	v_lshl_add_u64 v[198:199], v[212:213], 0, s[64:65]
	s_add_i32 m0, s22, 0x2000
	s_add_i32 s22, s54, s28
	global_load_lds_dwordx4 v[198:199], off
	v_lshl_add_u64 v[198:199], v[214:215], 0, s[64:65]
	s_mov_b32 m0, s22
	s_nop 0
	global_load_lds_dwordx4 v[198:199], off
	v_lshl_add_u64 v[198:199], v[216:217], 0, s[64:65]
	s_add_i32 m0, s22, 0x2000
	s_nop 0
	global_load_lds_dwordx4 v[198:199], off
	v_lshl_add_u64 v[198:199], v[218:219], 0, s[64:65]
	s_mov_b32 m0, s36
	s_nop 0
	global_load_lds_dwordx4 v[198:199], off
	v_lshl_add_u64 v[198:199], v[220:221], 0, s[64:65]
	s_mov_b32 m0, s37
	s_nop 0
	global_load_lds_dwordx4 v[198:199], off
	s_waitcnt vmcnt(8)
	s_waitcnt lgkmcnt(0)
	s_setprio 1
	s_barrier
	v_mfma_f32_16x16x32_bf16 v[60:63], v[142:145], v[174:177], v[60:63]
	v_mfma_f32_16x16x32_bf16 v[56:59], v[150:153], v[174:177], v[56:59]
	v_mfma_f32_16x16x32_bf16 v[44:47], v[142:145], v[182:185], v[44:47]
	v_mfma_f32_16x16x32_bf16 v[40:43], v[150:153], v[182:185], v[40:43]
	v_mfma_f32_16x16x32_bf16 v[28:31], v[142:145], v[190:193], v[28:31]
	v_mfma_f32_16x16x32_bf16 v[24:27], v[150:153], v[190:193], v[24:27]
	v_mfma_f32_16x16x32_bf16 v[12:15], v[142:145], v[202:205], v[12:15]
	v_mfma_f32_16x16x32_bf16 v[8:11], v[150:153], v[202:205], v[8:11]
	v_mfma_f32_16x16x32_bf16 v[60:63], v[146:149], v[178:181], v[60:63]
	v_mfma_f32_16x16x32_bf16 v[56:59], v[154:157], v[178:181], v[56:59]
	v_mfma_f32_16x16x32_bf16 v[44:47], v[146:149], v[186:189], v[44:47]
	v_mfma_f32_16x16x32_bf16 v[40:43], v[154:157], v[186:189], v[40:43]
	v_mfma_f32_16x16x32_bf16 v[28:31], v[146:149], v[194:197], v[28:31]
	v_mfma_f32_16x16x32_bf16 v[24:27], v[154:157], v[194:197], v[24:27]
	v_mfma_f32_16x16x32_bf16 v[12:15], v[146:149], v[206:209], v[12:15]
	v_mfma_f32_16x16x32_bf16 v[8:11], v[154:157], v[206:209], v[8:11]
	s_setprio 0
	s_setprio 1
	v_mfma_f32_16x16x32_bf16 v[52:55], v[158:161], v[174:177], v[52:55]
	v_mfma_f32_16x16x32_bf16 v[48:51], v[166:169], v[174:177], v[48:51]
	v_mfma_f32_16x16x32_bf16 v[36:39], v[158:161], v[182:185], v[36:39]
	v_mfma_f32_16x16x32_bf16 v[32:35], v[166:169], v[182:185], v[32:35]
	v_mfma_f32_16x16x32_bf16 v[20:23], v[158:161], v[190:193], v[20:23]
	v_mfma_f32_16x16x32_bf16 v[16:19], v[166:169], v[190:193], v[16:19]
	v_mfma_f32_16x16x32_bf16 v[4:7], v[158:161], v[202:205], v[4:7]
	v_mfma_f32_16x16x32_bf16 v[0:3], v[166:169], v[202:205], v[0:3]
	v_mfma_f32_16x16x32_bf16 v[52:55], v[162:165], v[178:181], v[52:55]
	v_mfma_f32_16x16x32_bf16 v[48:51], v[170:173], v[178:181], v[48:51]
	v_mfma_f32_16x16x32_bf16 v[36:39], v[162:165], v[186:189], v[36:39]
	v_mfma_f32_16x16x32_bf16 v[32:35], v[170:173], v[186:189], v[32:35]
	v_mfma_f32_16x16x32_bf16 v[20:23], v[162:165], v[194:197], v[20:23]
	v_mfma_f32_16x16x32_bf16 v[16:19], v[170:173], v[194:197], v[16:19]
	v_mfma_f32_16x16x32_bf16 v[4:7], v[162:165], v[206:209], v[4:7]
	v_mfma_f32_16x16x32_bf16 v[0:3], v[170:173], v[206:209], v[0:3]
	s_barrier
	s_setprio 0
	s_add_u32 s20, s20, 0x100
	s_addc_u32 s21, s21, 0
	s_add_u32 s49, s49, 0x100
	s_addc_u32 s50, s50, 0
	s_cmp_ge_i32 s51, s34
	s_mov_b32 s22, s51
	s_cbranch_scc0 .LBB0_1149
	s_movk_i32 s53, 0xc000
	s_mov_b64 s[54:55], 0x800

.LBB0_1249:
	s_add_u32 s4, s74, 0x100
	s_addc_u32 s5, s75, 0
	s_add_i32 s25, 0, 0x10000
	s_cmpk_eq_i32 s24, 0x54
	s_cselect_b32 vcc_hi, s81, s5
	s_cselect_b32 vcc_lo, s80, s4
	s_cselect_b32 s83, s79, s23
	s_cselect_b32 s82, s78, s7
	s_add_i32 s28, 0, 0x14000
	v_add_u32_e32 v92, s25, v213
	v_add_u32_e32 v124, s28, v213
	ds_read_b128 v[76:79], v92
	ds_read_b128 v[80:83], v92 offset:1024
	ds_read_b128 v[84:87], v92 offset:2048
	ds_read_b128 v[92:95], v92 offset:3072
	ds_read_b128 v[112:115], v124
	ds_read_b128 v[116:119], v124 offset:1024
	ds_read_b128 v[120:123], v124 offset:2048
	ds_read_b128 v[124:127], v124 offset:3072
	v_lshl_add_u64 v[192:193], s[74:75], 0, v[222:223]
	s_add_i32 m0, s85, 0xc000
	ds_read_b128 v[152:155], v206
	ds_read_b128 v[160:163], v206 offset:1024
	ds_read_b128 v[168:171], v206 offset:2048
	ds_read_b128 v[172:175], v206 offset:3072
	ds_read_b128 v[176:179], v206 offset:4096
	ds_read_b128 v[180:183], v206 offset:5120
	ds_read_b128 v[184:187], v206 offset:6144
	ds_read_b128 v[188:191], v206 offset:7168
	global_load_lds_dwordx4 v[192:193], off
	v_lshl_add_u64 v[192:193], s[74:75], 0, v[224:225]
	s_add_i32 m0, s85, 0xe000
	s_nop 0
	global_load_lds_dwordx4 v[192:193], off
	s_waitcnt vmcnt(8)
	s_waitcnt lgkmcnt(0)
	s_setprio 1
	s_barrier
	v_mfma_f32_16x16x32_bf16 v[164:167], v[76:79], v[152:155], v[164:167]
	v_mfma_f32_16x16x32_bf16 v[156:159], v[84:87], v[152:155], v[156:159]
	v_mfma_f32_16x16x32_bf16 v[148:151], v[76:79], v[168:171], v[148:151]
	v_mfma_f32_16x16x32_bf16 v[144:147], v[84:87], v[168:171], v[144:147]
	v_mfma_f32_16x16x32_bf16 v[140:143], v[76:79], v[176:179], v[140:143]
	v_mfma_f32_16x16x32_bf16 v[136:139], v[84:87], v[176:179], v[136:139]
	v_mfma_f32_16x16x32_bf16 v[132:135], v[76:79], v[184:187], v[132:135]
	v_mfma_f32_16x16x32_bf16 v[128:131], v[84:87], v[184:187], v[128:131]
	v_mfma_f32_16x16x32_bf16 v[164:167], v[80:83], v[160:163], v[164:167]
	v_mfma_f32_16x16x32_bf16 v[156:159], v[92:95], v[160:163], v[156:159]
	v_mfma_f32_16x16x32_bf16 v[148:151], v[80:83], v[172:175], v[148:151]
	v_mfma_f32_16x16x32_bf16 v[144:147], v[92:95], v[172:175], v[144:147]
	v_mfma_f32_16x16x32_bf16 v[140:143], v[80:83], v[180:183], v[140:143]
	v_mfma_f32_16x16x32_bf16 v[136:139], v[92:95], v[180:183], v[136:139]
	v_mfma_f32_16x16x32_bf16 v[132:135], v[80:83], v[188:191], v[132:135]
	v_mfma_f32_16x16x32_bf16 v[128:131], v[92:95], v[188:191], v[128:131]
	s_setprio 0
	s_setprio 1
	v_mfma_f32_16x16x32_bf16 v[108:111], v[112:115], v[152:155], v[108:111]
	v_mfma_f32_16x16x32_bf16 v[104:107], v[120:123], v[152:155], v[104:107]
	v_mfma_f32_16x16x32_bf16 v[100:103], v[112:115], v[168:171], v[100:103]
	v_mfma_f32_16x16x32_bf16 v[96:99], v[120:123], v[168:171], v[96:99]
	v_mfma_f32_16x16x32_bf16 v[88:91], v[112:115], v[176:179], v[88:91]
	v_mfma_f32_16x16x32_bf16 v[72:75], v[120:123], v[176:179], v[72:75]
	v_mfma_f32_16x16x32_bf16 v[68:71], v[112:115], v[184:187], v[68:71]
	v_mfma_f32_16x16x32_bf16 v[64:67], v[120:123], v[184:187], v[64:67]
	v_mfma_f32_16x16x32_bf16 v[108:111], v[116:119], v[160:163], v[108:111]
	v_mfma_f32_16x16x32_bf16 v[104:107], v[124:127], v[160:163], v[104:107]
	v_mfma_f32_16x16x32_bf16 v[100:103], v[116:119], v[172:175], v[100:103]
	v_mfma_f32_16x16x32_bf16 v[96:99], v[124:127], v[172:175], v[96:99]
	v_mfma_f32_16x16x32_bf16 v[88:91], v[116:119], v[180:183], v[88:91]
	v_mfma_f32_16x16x32_bf16 v[72:75], v[124:127], v[180:183], v[72:75]
	v_mfma_f32_16x16x32_bf16 v[68:71], v[116:119], v[188:191], v[68:71]
	v_mfma_f32_16x16x32_bf16 v[64:67], v[124:127], v[188:191], v[64:67]
	s_barrier
	s_setprio 0
	s_add_i32 s25, s25, s56
	v_lshl_add_u64 v[192:193], s[82:83], 0, v[216:217]
	s_mov_b32 m0, s25
	ds_read_b128 v[152:155], v206 offset:16384
	ds_read_b128 v[160:163], v206 offset:17408
	ds_read_b128 v[168:171], v206 offset:18432
	ds_read_b128 v[172:175], v206 offset:19456
	ds_read_b128 v[176:179], v206 offset:20480
	ds_read_b128 v[180:183], v206 offset:21504
	ds_read_b128 v[184:187], v206 offset:22528
	ds_read_b128 v[188:191], v206 offset:23552
	global_load_lds_dwordx4 v[192:193], off
	s_add_i32 m0, s25, 0x2000
	s_add_u32 s74, s82, 0x160000
	v_lshl_add_u64 v[194:195], s[82:83], 0, v[220:221]
	s_addc_u32 s75, s83, 0
	s_add_i32 s25, s28, s56
	global_load_lds_dwordx4 v[194:195], off
	v_lshl_add_u64 v[196:197], s[74:75], 0, v[216:217]
	s_mov_b32 m0, s25
	v_lshl_add_u64 v[198:199], vcc, 0, v[218:219]
	global_load_lds_dwordx4 v[196:197], off
	v_lshl_add_u64 v[196:197], s[74:75], 0, v[220:221]
	s_add_i32 m0, s25, 0x2000
	s_nop 0
	global_load_lds_dwordx4 v[196:197], off
	v_lshl_add_u64 v[196:197], vcc, 0, v[214:215]
	s_mov_b32 m0, s85
	s_nop 0
	global_load_lds_dwordx4 v[196:197], off
	s_mov_b32 m0, s53
	s_nop 0
	global_load_lds_dwordx4 v[198:199], off
	s_waitcnt vmcnt(8)
	s_waitcnt lgkmcnt(0)
	s_setprio 1
	s_barrier
	v_mfma_f32_16x16x32_bf16 v[60:63], v[76:79], v[152:155], v[60:63]
	v_mfma_f32_16x16x32_bf16 v[56:59], v[84:87], v[152:155], v[56:59]
	v_mfma_f32_16x16x32_bf16 v[52:55], v[76:79], v[168:171], v[52:55]
	v_mfma_f32_16x16x32_bf16 v[48:51], v[84:87], v[168:171], v[48:51]
	v_mfma_f32_16x16x32_bf16 v[44:47], v[76:79], v[176:179], v[44:47]
	v_mfma_f32_16x16x32_bf16 v[40:43], v[84:87], v[176:179], v[40:43]
	v_mfma_f32_16x16x32_bf16 v[36:39], v[76:79], v[184:187], v[36:39]
	v_mfma_f32_16x16x32_bf16 v[32:35], v[84:87], v[184:187], v[32:35]
	v_mfma_f32_16x16x32_bf16 v[60:63], v[80:83], v[160:163], v[60:63]
	v_mfma_f32_16x16x32_bf16 v[56:59], v[92:95], v[160:163], v[56:59]
	v_mfma_f32_16x16x32_bf16 v[52:55], v[80:83], v[172:175], v[52:55]
	v_mfma_f32_16x16x32_bf16 v[48:51], v[92:95], v[172:175], v[48:51]
	v_mfma_f32_16x16x32_bf16 v[44:47], v[80:83], v[180:183], v[44:47]
	v_mfma_f32_16x16x32_bf16 v[40:43], v[92:95], v[180:183], v[40:43]
	v_mfma_f32_16x16x32_bf16 v[36:39], v[80:83], v[188:191], v[36:39]
	v_mfma_f32_16x16x32_bf16 v[32:35], v[92:95], v[188:191], v[32:35]
	s_setprio 0
	s_setprio 1
	v_mfma_f32_16x16x32_bf16 v[28:31], v[112:115], v[152:155], v[28:31]
	v_mfma_f32_16x16x32_bf16 v[24:27], v[120:123], v[152:155], v[24:27]
	v_mfma_f32_16x16x32_bf16 v[20:23], v[112:115], v[168:171], v[20:23]
	v_mfma_f32_16x16x32_bf16 v[16:19], v[120:123], v[168:171], v[16:19]
	v_mfma_f32_16x16x32_bf16 v[12:15], v[112:115], v[176:179], v[12:15]
	v_mfma_f32_16x16x32_bf16 v[8:11], v[120:123], v[176:179], v[8:11]
	v_mfma_f32_16x16x32_bf16 v[4:7], v[112:115], v[184:187], v[4:7]
	v_mfma_f32_16x16x32_bf16 v[0:3], v[120:123], v[184:187], v[0:3]
	v_mfma_f32_16x16x32_bf16 v[28:31], v[116:119], v[160:163], v[28:31]
	v_mfma_f32_16x16x32_bf16 v[24:27], v[124:127], v[160:163], v[24:27]
	v_mfma_f32_16x16x32_bf16 v[20:23], v[116:119], v[172:175], v[20:23]
	v_mfma_f32_16x16x32_bf16 v[16:19], v[124:127], v[172:175], v[16:19]
	v_mfma_f32_16x16x32_bf16 v[12:15], v[116:119], v[180:183], v[12:15]
	v_mfma_f32_16x16x32_bf16 v[8:11], v[124:127], v[180:183], v[8:11]
	v_mfma_f32_16x16x32_bf16 v[4:7], v[116:119], v[188:191], v[4:7]
	v_mfma_f32_16x16x32_bf16 v[0:3], v[124:127], v[188:191], v[0:3]
	s_barrier
	s_setprio 0
	s_add_i32 s25, 0, 0x18000
	s_add_i32 s28, 0, 0x1c000
	v_add_u32_e32 v92, s25, v213
	v_add_u32_e32 v124, s28, v213
	ds_read_b128 v[76:79], v92
	ds_read_b128 v[80:83], v92 offset:1024
	ds_read_b128 v[84:87], v92 offset:2048
	ds_read_b128 v[92:95], v92 offset:3072
	ds_read_b128 v[112:115], v124
	ds_read_b128 v[116:119], v124 offset:1024
	ds_read_b128 v[120:123], v124 offset:2048
	ds_read_b128 v[124:127], v124 offset:3072
	s_add_u32 s74, vcc_lo, 0x160000
	s_addc_u32 s75, vcc_hi, 0
	s_mov_b32 m0, s84
	v_lshl_add_u64 v[202:203], s[74:75], 0, v[214:215]
	ds_read_b128 v[152:155], v206 offset:32768
	ds_read_b128 v[160:163], v206 offset:33792
	ds_read_b128 v[168:171], v206 offset:34816
	ds_read_b128 v[172:175], v206 offset:35840
	ds_read_b128 v[176:179], v206 offset:36864
	ds_read_b128 v[180:183], v206 offset:37888
	ds_read_b128 v[184:187], v206 offset:38912
	ds_read_b128 v[188:191], v206 offset:39936
	global_load_lds_dwordx4 v[202:203], off
	v_lshl_add_u64 v[202:203], s[74:75], 0, v[218:219]
	s_mov_b32 m0, s26
	s_nop 0
	global_load_lds_dwordx4 v[202:203], off
	s_waitcnt vmcnt(8)
	s_waitcnt lgkmcnt(0)
	s_setprio 1
	s_barrier
	v_mfma_f32_16x16x32_bf16 v[164:167], v[76:79], v[152:155], v[164:167]
	v_mfma_f32_16x16x32_bf16 v[156:159], v[84:87], v[152:155], v[156:159]
	v_mfma_f32_16x16x32_bf16 v[148:151], v[76:79], v[168:171], v[148:151]
	v_mfma_f32_16x16x32_bf16 v[144:147], v[84:87], v[168:171], v[144:147]
	v_mfma_f32_16x16x32_bf16 v[140:143], v[76:79], v[176:179], v[140:143]
	v_mfma_f32_16x16x32_bf16 v[136:139], v[84:87], v[176:179], v[136:139]
	v_mfma_f32_16x16x32_bf16 v[132:135], v[76:79], v[184:187], v[132:135]
	v_mfma_f32_16x16x32_bf16 v[128:131], v[84:87], v[184:187], v[128:131]
	v_mfma_f32_16x16x32_bf16 v[164:167], v[80:83], v[160:163], v[164:167]
	v_mfma_f32_16x16x32_bf16 v[156:159], v[92:95], v[160:163], v[156:159]
	v_mfma_f32_16x16x32_bf16 v[148:151], v[80:83], v[172:175], v[148:151]
	v_mfma_f32_16x16x32_bf16 v[144:147], v[92:95], v[172:175], v[144:147]
	v_mfma_f32_16x16x32_bf16 v[140:143], v[80:83], v[180:183], v[140:143]
	v_mfma_f32_16x16x32_bf16 v[136:139], v[92:95], v[180:183], v[136:139]
	v_mfma_f32_16x16x32_bf16 v[132:135], v[80:83], v[188:191], v[132:135]
	v_mfma_f32_16x16x32_bf16 v[128:131], v[92:95], v[188:191], v[128:131]
	s_setprio 0
	s_setprio 1
	v_mfma_f32_16x16x32_bf16 v[108:111], v[112:115], v[152:155], v[108:111]
	v_mfma_f32_16x16x32_bf16 v[104:107], v[120:123], v[152:155], v[104:107]
	v_mfma_f32_16x16x32_bf16 v[100:103], v[112:115], v[168:171], v[100:103]
	v_mfma_f32_16x16x32_bf16 v[96:99], v[120:123], v[168:171], v[96:99]
	v_mfma_f32_16x16x32_bf16 v[88:91], v[112:115], v[176:179], v[88:91]
	v_mfma_f32_16x16x32_bf16 v[72:75], v[120:123], v[176:179], v[72:75]
	v_mfma_f32_16x16x32_bf16 v[68:71], v[112:115], v[184:187], v[68:71]
	v_mfma_f32_16x16x32_bf16 v[64:67], v[120:123], v[184:187], v[64:67]
	v_mfma_f32_16x16x32_bf16 v[108:111], v[116:119], v[160:163], v[108:111]
	v_mfma_f32_16x16x32_bf16 v[104:107], v[124:127], v[160:163], v[104:107]
	v_mfma_f32_16x16x32_bf16 v[100:103], v[116:119], v[172:175], v[100:103]
	v_mfma_f32_16x16x32_bf16 v[96:99], v[124:127], v[172:175], v[96:99]
	v_mfma_f32_16x16x32_bf16 v[88:91], v[116:119], v[180:183], v[88:91]
	v_mfma_f32_16x16x32_bf16 v[72:75], v[124:127], v[180:183], v[72:75]
	v_mfma_f32_16x16x32_bf16 v[68:71], v[116:119], v[188:191], v[68:71]
	v_mfma_f32_16x16x32_bf16 v[64:67], v[124:127], v[188:191], v[64:67]
	s_barrier
	s_setprio 0
	s_add_i32 s25, s25, s56
	v_lshl_add_u64 v[192:193], v[192:193], 0, s[64:65]
	s_mov_b32 m0, s25
	ds_read_b128 v[152:155], v206 offset:49152
	ds_read_b128 v[160:163], v206 offset:50176
	ds_read_b128 v[168:171], v206 offset:51200
	ds_read_b128 v[172:175], v206 offset:52224
	ds_read_b128 v[176:179], v206 offset:53248
	ds_read_b128 v[180:183], v206 offset:54272
	ds_read_b128 v[184:187], v206 offset:55296
	ds_read_b128 v[188:191], v206 offset:56320
	global_load_lds_dwordx4 v[192:193], off
	s_add_i32 m0, s25, 0x2000
	s_add_u32 s74, s82, 0x160080
	v_lshl_add_u64 v[192:193], v[194:195], 0, s[64:65]
	s_addc_u32 s75, s83, 0
	s_add_i32 s25, s28, s56
	global_load_lds_dwordx4 v[192:193], off
	v_lshl_add_u64 v[192:193], s[74:75], 0, v[216:217]
	s_mov_b32 m0, s25
	s_nop 0
	global_load_lds_dwordx4 v[192:193], off
	v_lshl_add_u64 v[192:193], s[74:75], 0, v[220:221]
	s_add_i32 m0, s25, 0x2000
	s_nop 0
	global_load_lds_dwordx4 v[192:193], off
	v_lshl_add_u64 v[192:193], v[196:197], 0, s[64:65]
	s_mov_b32 m0, s27
	s_nop 0
	global_load_lds_dwordx4 v[192:193], off
	v_lshl_add_u64 v[192:193], v[198:199], 0, s[64:65]
	s_mov_b32 m0, s42
	s_nop 0
	global_load_lds_dwordx4 v[192:193], off
	s_waitcnt vmcnt(8)
	s_waitcnt lgkmcnt(0)
	s_setprio 1
	s_barrier
	v_mfma_f32_16x16x32_bf16 v[60:63], v[76:79], v[152:155], v[60:63]
	v_mfma_f32_16x16x32_bf16 v[56:59], v[84:87], v[152:155], v[56:59]
	v_mfma_f32_16x16x32_bf16 v[52:55], v[76:79], v[168:171], v[52:55]
	v_mfma_f32_16x16x32_bf16 v[48:51], v[84:87], v[168:171], v[48:51]
	v_mfma_f32_16x16x32_bf16 v[44:47], v[76:79], v[176:179], v[44:47]
	v_mfma_f32_16x16x32_bf16 v[40:43], v[84:87], v[176:179], v[40:43]
	v_mfma_f32_16x16x32_bf16 v[36:39], v[76:79], v[184:187], v[36:39]
	v_mfma_f32_16x16x32_bf16 v[32:35], v[84:87], v[184:187], v[32:35]
	v_mfma_f32_16x16x32_bf16 v[60:63], v[80:83], v[160:163], v[60:63]
	v_mfma_f32_16x16x32_bf16 v[56:59], v[92:95], v[160:163], v[56:59]
	v_mfma_f32_16x16x32_bf16 v[52:55], v[80:83], v[172:175], v[52:55]
	v_mfma_f32_16x16x32_bf16 v[48:51], v[92:95], v[172:175], v[48:51]
	v_mfma_f32_16x16x32_bf16 v[44:47], v[80:83], v[180:183], v[44:47]
	v_mfma_f32_16x16x32_bf16 v[40:43], v[92:95], v[180:183], v[40:43]
	v_mfma_f32_16x16x32_bf16 v[36:39], v[80:83], v[188:191], v[36:39]
	v_mfma_f32_16x16x32_bf16 v[32:35], v[92:95], v[188:191], v[32:35]
	s_setprio 0
	s_setprio 1
	v_mfma_f32_16x16x32_bf16 v[28:31], v[112:115], v[152:155], v[28:31]
	v_mfma_f32_16x16x32_bf16 v[24:27], v[120:123], v[152:155], v[24:27]
	v_mfma_f32_16x16x32_bf16 v[20:23], v[112:115], v[168:171], v[20:23]
	v_mfma_f32_16x16x32_bf16 v[16:19], v[120:123], v[168:171], v[16:19]
	v_mfma_f32_16x16x32_bf16 v[12:15], v[112:115], v[176:179], v[12:15]
	v_mfma_f32_16x16x32_bf16 v[8:11], v[120:123], v[176:179], v[8:11]
	v_mfma_f32_16x16x32_bf16 v[4:7], v[112:115], v[184:187], v[4:7]
	v_mfma_f32_16x16x32_bf16 v[0:3], v[120:123], v[184:187], v[0:3]
	v_mfma_f32_16x16x32_bf16 v[28:31], v[116:119], v[160:163], v[28:31]
	v_mfma_f32_16x16x32_bf16 v[24:27], v[124:127], v[160:163], v[24:27]
	v_mfma_f32_16x16x32_bf16 v[20:23], v[116:119], v[172:175], v[20:23]
	v_mfma_f32_16x16x32_bf16 v[16:19], v[124:127], v[172:175], v[16:19]
	v_mfma_f32_16x16x32_bf16 v[12:15], v[116:119], v[180:183], v[12:15]
	v_mfma_f32_16x16x32_bf16 v[8:11], v[124:127], v[180:183], v[8:11]
	v_mfma_f32_16x16x32_bf16 v[4:7], v[116:119], v[188:191], v[4:7]
	v_mfma_f32_16x16x32_bf16 v[0:3], v[124:127], v[188:191], v[0:3]
	s_barrier
	s_setprio 0
	s_add_i32 s24, s24, 2
	s_add_u32 s7, s7, 0x100
	s_addc_u32 s23, s23, 0
	s_cmpk_gt_u32 s24, 0x55
	s_mov_b64 s[74:75], s[4:5]
	s_cbranch_scc0 .LBB0_1249
	v_readlane_b32 s4, v254, 60
	v_readlane_b32 s5, v254, 61
	s_and_b64 vcc, exec, s[4:5]
	s_cbranch_vccz .LBB0_1252
	s_barrier

.LBB0_1366:
	s_add_u32 s74, s72, 0xfff80080
	s_addc_u32 s75, s73, -1
	s_add_i32 vcc_lo, 0, 0x10000
	s_cmp_eq_u32 s84, 28
	s_cselect_b32 s79, s5, s75
	s_cselect_b32 s78, s42, s74
	s_cselect_b32 s75, s43, s69
	s_cselect_b32 s74, s55, s67
	s_add_i32 s8, 0, 0x14000
	v_add_u32_e32 v116, vcc_lo, v203
	v_add_u32_e32 v136, s8, v203
	ds_read_b128 v[104:107], v116
	ds_read_b128 v[108:111], v116 offset:1024
	ds_read_b128 v[112:115], v116 offset:2048
	ds_read_b128 v[116:119], v116 offset:3072
	ds_read_b128 v[124:127], v136
	ds_read_b128 v[128:131], v136 offset:1024
	ds_read_b128 v[132:135], v136 offset:2048
	ds_read_b128 v[136:139], v136 offset:3072
	v_lshl_add_u64 v[206:207], s[72:73], 0, v[214:215]
	s_add_i32 m0, s85, 0xc000
	ds_read_b128 v[160:163], v204
	ds_read_b128 v[164:167], v204 offset:1024
	ds_read_b128 v[168:171], v204 offset:2048
	ds_read_b128 v[172:175], v204 offset:3072
	ds_read_b128 v[176:179], v204 offset:4096
	ds_read_b128 v[180:183], v204 offset:5120
	ds_read_b128 v[184:187], v204 offset:6144
	ds_read_b128 v[188:191], v204 offset:7168
	global_load_lds_dwordx4 v[206:207], off
	v_lshl_add_u64 v[206:207], s[72:73], 0, v[216:217]
	s_add_i32 m0, s85, 0xe000
	s_nop 0
	global_load_lds_dwordx4 v[206:207], off
	s_waitcnt vmcnt(8)
	s_waitcnt lgkmcnt(0)
	s_setprio 1
	s_barrier
	v_mfma_f32_16x16x32_bf16 v[156:159], v[104:107], v[160:163], v[156:159]
	v_mfma_f32_16x16x32_bf16 v[152:155], v[112:115], v[160:163], v[152:155]
	v_mfma_f32_16x16x32_bf16 v[148:151], v[104:107], v[168:171], v[148:151]
	v_mfma_f32_16x16x32_bf16 v[144:147], v[112:115], v[168:171], v[144:147]
	v_mfma_f32_16x16x32_bf16 v[140:143], v[104:107], v[176:179], v[140:143]
	v_mfma_f32_16x16x32_bf16 v[120:123], v[112:115], v[176:179], v[120:123]
	v_mfma_f32_16x16x32_bf16 v[100:103], v[104:107], v[184:187], v[100:103]
	v_mfma_f32_16x16x32_bf16 v[96:99], v[112:115], v[184:187], v[96:99]
	v_mfma_f32_16x16x32_bf16 v[156:159], v[108:111], v[164:167], v[156:159]
	v_mfma_f32_16x16x32_bf16 v[152:155], v[116:119], v[164:167], v[152:155]
	v_mfma_f32_16x16x32_bf16 v[148:151], v[108:111], v[172:175], v[148:151]
	v_mfma_f32_16x16x32_bf16 v[144:147], v[116:119], v[172:175], v[144:147]
	v_mfma_f32_16x16x32_bf16 v[140:143], v[108:111], v[180:183], v[140:143]
	v_mfma_f32_16x16x32_bf16 v[120:123], v[116:119], v[180:183], v[120:123]
	v_mfma_f32_16x16x32_bf16 v[100:103], v[108:111], v[188:191], v[100:103]
	v_mfma_f32_16x16x32_bf16 v[96:99], v[116:119], v[188:191], v[96:99]
	s_setprio 0
	s_setprio 1
	v_mfma_f32_16x16x32_bf16 v[60:63], v[124:127], v[160:163], v[60:63]
	v_mfma_f32_16x16x32_bf16 v[56:59], v[132:135], v[160:163], v[56:59]
	v_mfma_f32_16x16x32_bf16 v[52:55], v[124:127], v[168:171], v[52:55]
	v_mfma_f32_16x16x32_bf16 v[48:51], v[132:135], v[168:171], v[48:51]
	v_mfma_f32_16x16x32_bf16 v[44:47], v[124:127], v[176:179], v[44:47]
	v_mfma_f32_16x16x32_bf16 v[40:43], v[132:135], v[176:179], v[40:43]
	v_mfma_f32_16x16x32_bf16 v[36:39], v[124:127], v[184:187], v[36:39]
	v_mfma_f32_16x16x32_bf16 v[32:35], v[132:135], v[184:187], v[32:35]
	v_mfma_f32_16x16x32_bf16 v[60:63], v[128:131], v[164:167], v[60:63]
	v_mfma_f32_16x16x32_bf16 v[56:59], v[136:139], v[164:167], v[56:59]
	v_mfma_f32_16x16x32_bf16 v[52:55], v[128:131], v[172:175], v[52:55]
	v_mfma_f32_16x16x32_bf16 v[48:51], v[136:139], v[172:175], v[48:51]
	v_mfma_f32_16x16x32_bf16 v[44:47], v[128:131], v[180:183], v[44:47]
	v_mfma_f32_16x16x32_bf16 v[40:43], v[136:139], v[180:183], v[40:43]
	v_mfma_f32_16x16x32_bf16 v[36:39], v[128:131], v[188:191], v[36:39]
	v_mfma_f32_16x16x32_bf16 v[32:35], v[136:139], v[188:191], v[32:35]
	s_barrier
	s_setprio 0
	s_add_i32 s9, vcc_lo, s81
	v_lshl_add_u64 v[206:207], s[74:75], 0, v[194:195]
	s_mov_b32 m0, s9
	ds_read_b128 v[160:163], v204 offset:16384
	ds_read_b128 v[164:167], v204 offset:17408
	ds_read_b128 v[168:171], v204 offset:18432
	ds_read_b128 v[172:175], v204 offset:19456
	ds_read_b128 v[176:179], v204 offset:20480
	ds_read_b128 v[180:183], v204 offset:21504
	ds_read_b128 v[184:187], v204 offset:22528
	ds_read_b128 v[188:191], v204 offset:23552
	global_load_lds_dwordx4 v[206:207], off
	s_add_i32 m0, s9, 0x2000
	s_add_u32 vcc_lo, s74, 0x80000
	v_lshl_add_u64 v[208:209], s[74:75], 0, v[198:199]
	s_addc_u32 vcc_hi, s75, 0
	s_add_i32 s8, s8, s81
	global_load_lds_dwordx4 v[208:209], off
	v_lshl_add_u64 v[212:213], vcc, 0, v[194:195]
	s_mov_b32 m0, s8
	v_lshl_add_u64 v[218:219], s[78:79], 0, v[196:197]
	global_load_lds_dwordx4 v[212:213], off
	v_lshl_add_u64 v[212:213], vcc, 0, v[198:199]
	s_add_i32 m0, s8, 0x2000
	s_nop 0
	global_load_lds_dwordx4 v[212:213], off
	v_lshl_add_u64 v[212:213], s[78:79], 0, v[192:193]
	s_mov_b32 m0, s85
	s_nop 0
	global_load_lds_dwordx4 v[212:213], off
	s_mov_b32 m0, s38
	s_nop 0
	global_load_lds_dwordx4 v[218:219], off
	s_waitcnt vmcnt(8)
	s_waitcnt lgkmcnt(0)
	s_setprio 1
	s_barrier
	v_mfma_f32_16x16x32_bf16 v[92:95], v[104:107], v[160:163], v[92:95]
	v_mfma_f32_16x16x32_bf16 v[88:91], v[112:115], v[160:163], v[88:91]
	v_mfma_f32_16x16x32_bf16 v[84:87], v[104:107], v[168:171], v[84:87]
	v_mfma_f32_16x16x32_bf16 v[80:83], v[112:115], v[168:171], v[80:83]
	v_mfma_f32_16x16x32_bf16 v[76:79], v[104:107], v[176:179], v[76:79]
	v_mfma_f32_16x16x32_bf16 v[72:75], v[112:115], v[176:179], v[72:75]
	v_mfma_f32_16x16x32_bf16 v[68:71], v[104:107], v[184:187], v[68:71]
	v_mfma_f32_16x16x32_bf16 v[64:67], v[112:115], v[184:187], v[64:67]
	v_mfma_f32_16x16x32_bf16 v[92:95], v[108:111], v[164:167], v[92:95]
	v_mfma_f32_16x16x32_bf16 v[88:91], v[116:119], v[164:167], v[88:91]
	v_mfma_f32_16x16x32_bf16 v[84:87], v[108:111], v[172:175], v[84:87]
	v_mfma_f32_16x16x32_bf16 v[80:83], v[116:119], v[172:175], v[80:83]
	v_mfma_f32_16x16x32_bf16 v[76:79], v[108:111], v[180:183], v[76:79]
	v_mfma_f32_16x16x32_bf16 v[72:75], v[116:119], v[180:183], v[72:75]
	v_mfma_f32_16x16x32_bf16 v[68:71], v[108:111], v[188:191], v[68:71]
	v_mfma_f32_16x16x32_bf16 v[64:67], v[116:119], v[188:191], v[64:67]
	s_setprio 0
	s_setprio 1
	v_mfma_f32_16x16x32_bf16 v[28:31], v[124:127], v[160:163], v[28:31]
	v_mfma_f32_16x16x32_bf16 v[24:27], v[132:135], v[160:163], v[24:27]
	v_mfma_f32_16x16x32_bf16 v[20:23], v[124:127], v[168:171], v[20:23]
	v_mfma_f32_16x16x32_bf16 v[16:19], v[132:135], v[168:171], v[16:19]
	v_mfma_f32_16x16x32_bf16 v[12:15], v[124:127], v[176:179], v[12:15]
	v_mfma_f32_16x16x32_bf16 v[8:11], v[132:135], v[176:179], v[8:11]
	v_mfma_f32_16x16x32_bf16 v[4:7], v[124:127], v[184:187], v[4:7]
	v_mfma_f32_16x16x32_bf16 v[0:3], v[132:135], v[184:187], v[0:3]
	v_mfma_f32_16x16x32_bf16 v[28:31], v[128:131], v[164:167], v[28:31]
	v_mfma_f32_16x16x32_bf16 v[24:27], v[136:139], v[164:167], v[24:27]
	v_mfma_f32_16x16x32_bf16 v[20:23], v[128:131], v[172:175], v[20:23]
	v_mfma_f32_16x16x32_bf16 v[16:19], v[136:139], v[172:175], v[16:19]
	v_mfma_f32_16x16x32_bf16 v[12:15], v[128:131], v[180:183], v[12:15]
	v_mfma_f32_16x16x32_bf16 v[8:11], v[136:139], v[180:183], v[8:11]
	v_mfma_f32_16x16x32_bf16 v[4:7], v[128:131], v[188:191], v[4:7]
	v_mfma_f32_16x16x32_bf16 v[0:3], v[136:139], v[188:191], v[0:3]
	s_barrier
	s_setprio 0
	s_add_i32 s8, 0, 0x18000
	s_add_i32 s9, 0, 0x1c000
	v_add_u32_e32 v116, s8, v203
	v_add_u32_e32 v136, s9, v203
	ds_read_b128 v[104:107], v116
	ds_read_b128 v[108:111], v116 offset:1024
	ds_read_b128 v[112:115], v116 offset:2048
	ds_read_b128 v[116:119], v116 offset:3072
	ds_read_b128 v[124:127], v136
	ds_read_b128 v[128:131], v136 offset:1024
	ds_read_b128 v[132:135], v136 offset:2048
	ds_read_b128 v[136:139], v136 offset:3072
	s_add_u32 s78, s78, 0x80000
	s_addc_u32 s79, s79, 0
	s_mov_b32 m0, s39
	v_lshl_add_u64 v[220:221], s[78:79], 0, v[192:193]
	ds_read_b128 v[160:163], v204 offset:32768
	ds_read_b128 v[164:167], v204 offset:33792
	ds_read_b128 v[168:171], v204 offset:34816
	ds_read_b128 v[172:175], v204 offset:35840
	ds_read_b128 v[176:179], v204 offset:36864
	ds_read_b128 v[180:183], v204 offset:37888
	ds_read_b128 v[184:187], v204 offset:38912
	ds_read_b128 v[188:191], v204 offset:39936
	global_load_lds_dwordx4 v[220:221], off
	v_lshl_add_u64 v[220:221], s[78:79], 0, v[196:197]
	s_mov_b32 m0, s94
	s_nop 0
	global_load_lds_dwordx4 v[220:221], off
	s_waitcnt vmcnt(8)
	s_waitcnt lgkmcnt(0)
	s_setprio 1
	s_barrier
	v_mfma_f32_16x16x32_bf16 v[156:159], v[104:107], v[160:163], v[156:159]
	v_mfma_f32_16x16x32_bf16 v[152:155], v[112:115], v[160:163], v[152:155]
	v_mfma_f32_16x16x32_bf16 v[148:151], v[104:107], v[168:171], v[148:151]
	v_mfma_f32_16x16x32_bf16 v[144:147], v[112:115], v[168:171], v[144:147]
	v_mfma_f32_16x16x32_bf16 v[140:143], v[104:107], v[176:179], v[140:143]
	v_mfma_f32_16x16x32_bf16 v[120:123], v[112:115], v[176:179], v[120:123]
	v_mfma_f32_16x16x32_bf16 v[100:103], v[104:107], v[184:187], v[100:103]
	v_mfma_f32_16x16x32_bf16 v[96:99], v[112:115], v[184:187], v[96:99]
	v_mfma_f32_16x16x32_bf16 v[156:159], v[108:111], v[164:167], v[156:159]
	v_mfma_f32_16x16x32_bf16 v[152:155], v[116:119], v[164:167], v[152:155]
	v_mfma_f32_16x16x32_bf16 v[148:151], v[108:111], v[172:175], v[148:151]
	v_mfma_f32_16x16x32_bf16 v[144:147], v[116:119], v[172:175], v[144:147]
	v_mfma_f32_16x16x32_bf16 v[140:143], v[108:111], v[180:183], v[140:143]
	v_mfma_f32_16x16x32_bf16 v[120:123], v[116:119], v[180:183], v[120:123]
	v_mfma_f32_16x16x32_bf16 v[100:103], v[108:111], v[188:191], v[100:103]
	v_mfma_f32_16x16x32_bf16 v[96:99], v[116:119], v[188:191], v[96:99]
	s_setprio 0
	s_setprio 1
	v_mfma_f32_16x16x32_bf16 v[60:63], v[124:127], v[160:163], v[60:63]
	v_mfma_f32_16x16x32_bf16 v[56:59], v[132:135], v[160:163], v[56:59]
	v_mfma_f32_16x16x32_bf16 v[52:55], v[124:127], v[168:171], v[52:55]
	v_mfma_f32_16x16x32_bf16 v[48:51], v[132:135], v[168:171], v[48:51]
	v_mfma_f32_16x16x32_bf16 v[44:47], v[124:127], v[176:179], v[44:47]
	v_mfma_f32_16x16x32_bf16 v[40:43], v[132:135], v[176:179], v[40:43]
	v_mfma_f32_16x16x32_bf16 v[36:39], v[124:127], v[184:187], v[36:39]
	v_mfma_f32_16x16x32_bf16 v[32:35], v[132:135], v[184:187], v[32:35]
	v_mfma_f32_16x16x32_bf16 v[60:63], v[128:131], v[164:167], v[60:63]
	v_mfma_f32_16x16x32_bf16 v[56:59], v[136:139], v[164:167], v[56:59]
	v_mfma_f32_16x16x32_bf16 v[52:55], v[128:131], v[172:175], v[52:55]
	v_mfma_f32_16x16x32_bf16 v[48:51], v[136:139], v[172:175], v[48:51]
	v_mfma_f32_16x16x32_bf16 v[44:47], v[128:131], v[180:183], v[44:47]
	v_mfma_f32_16x16x32_bf16 v[40:43], v[136:139], v[180:183], v[40:43]
	v_mfma_f32_16x16x32_bf16 v[36:39], v[128:131], v[188:191], v[36:39]
	v_mfma_f32_16x16x32_bf16 v[32:35], v[136:139], v[188:191], v[32:35]
	s_barrier
	s_setprio 0
	s_add_i32 s8, s8, s81
	v_lshl_add_u64 v[206:207], v[206:207], 0, s[64:65]
	s_mov_b32 m0, s8
	ds_read_b128 v[160:163], v204 offset:49152
	ds_read_b128 v[164:167], v204 offset:50176
	ds_read_b128 v[168:171], v204 offset:51200
	ds_read_b128 v[172:175], v204 offset:52224
	ds_read_b128 v[176:179], v204 offset:53248
	ds_read_b128 v[180:183], v204 offset:54272
	ds_read_b128 v[184:187], v204 offset:55296
	ds_read_b128 v[188:191], v204 offset:56320
	global_load_lds_dwordx4 v[206:207], off
	s_add_i32 m0, s8, 0x2000
	s_add_u32 s74, s74, 0x80080
	v_lshl_add_u64 v[206:207], v[208:209], 0, s[64:65]
	s_addc_u32 s75, s75, 0
	s_add_i32 s8, s9, s81
	global_load_lds_dwordx4 v[206:207], off
	v_lshl_add_u64 v[206:207], s[74:75], 0, v[194:195]
	s_mov_b32 m0, s8
	s_nop 0
	global_load_lds_dwordx4 v[206:207], off
	v_lshl_add_u64 v[206:207], s[74:75], 0, v[198:199]
	s_add_i32 m0, s8, 0x2000
	s_nop 0
	global_load_lds_dwordx4 v[206:207], off
	v_lshl_add_u64 v[206:207], v[212:213], 0, s[64:65]
	s_mov_b32 m0, s12
	s_nop 0
	global_load_lds_dwordx4 v[206:207], off
	v_lshl_add_u64 v[206:207], v[218:219], 0, s[64:65]
	s_mov_b32 m0, s13
	s_nop 0
	global_load_lds_dwordx4 v[206:207], off
	s_waitcnt vmcnt(8)
	s_waitcnt lgkmcnt(0)
	s_setprio 1
	s_barrier
	v_mfma_f32_16x16x32_bf16 v[92:95], v[104:107], v[160:163], v[92:95]
	v_mfma_f32_16x16x32_bf16 v[88:91], v[112:115], v[160:163], v[88:91]
	v_mfma_f32_16x16x32_bf16 v[84:87], v[104:107], v[168:171], v[84:87]
	v_mfma_f32_16x16x32_bf16 v[80:83], v[112:115], v[168:171], v[80:83]
	v_mfma_f32_16x16x32_bf16 v[76:79], v[104:107], v[176:179], v[76:79]
	v_mfma_f32_16x16x32_bf16 v[72:75], v[112:115], v[176:179], v[72:75]
	v_mfma_f32_16x16x32_bf16 v[68:71], v[104:107], v[184:187], v[68:71]
	v_mfma_f32_16x16x32_bf16 v[64:67], v[112:115], v[184:187], v[64:67]
	v_mfma_f32_16x16x32_bf16 v[92:95], v[108:111], v[164:167], v[92:95]
	v_mfma_f32_16x16x32_bf16 v[88:91], v[116:119], v[164:167], v[88:91]
	v_mfma_f32_16x16x32_bf16 v[84:87], v[108:111], v[172:175], v[84:87]
	v_mfma_f32_16x16x32_bf16 v[80:83], v[116:119], v[172:175], v[80:83]
	v_mfma_f32_16x16x32_bf16 v[76:79], v[108:111], v[180:183], v[76:79]
	v_mfma_f32_16x16x32_bf16 v[72:75], v[116:119], v[180:183], v[72:75]
	v_mfma_f32_16x16x32_bf16 v[68:71], v[108:111], v[188:191], v[68:71]
	v_mfma_f32_16x16x32_bf16 v[64:67], v[116:119], v[188:191], v[64:67]
	s_setprio 0
	s_setprio 1
	v_mfma_f32_16x16x32_bf16 v[28:31], v[124:127], v[160:163], v[28:31]
	v_mfma_f32_16x16x32_bf16 v[24:27], v[132:135], v[160:163], v[24:27]
	v_mfma_f32_16x16x32_bf16 v[20:23], v[124:127], v[168:171], v[20:23]
	v_mfma_f32_16x16x32_bf16 v[16:19], v[132:135], v[168:171], v[16:19]
	v_mfma_f32_16x16x32_bf16 v[12:15], v[124:127], v[176:179], v[12:15]
	v_mfma_f32_16x16x32_bf16 v[8:11], v[132:135], v[176:179], v[8:11]
	v_mfma_f32_16x16x32_bf16 v[4:7], v[124:127], v[184:187], v[4:7]
	v_mfma_f32_16x16x32_bf16 v[0:3], v[132:135], v[184:187], v[0:3]
	v_mfma_f32_16x16x32_bf16 v[28:31], v[128:131], v[164:167], v[28:31]
	v_mfma_f32_16x16x32_bf16 v[24:27], v[136:139], v[164:167], v[24:27]
	v_mfma_f32_16x16x32_bf16 v[20:23], v[128:131], v[172:175], v[20:23]
	v_mfma_f32_16x16x32_bf16 v[16:19], v[136:139], v[172:175], v[16:19]
	v_mfma_f32_16x16x32_bf16 v[12:15], v[128:131], v[180:183], v[12:15]
	v_mfma_f32_16x16x32_bf16 v[8:11], v[136:139], v[180:183], v[8:11]
	v_mfma_f32_16x16x32_bf16 v[4:7], v[128:131], v[188:191], v[4:7]
	v_mfma_f32_16x16x32_bf16 v[0:3], v[136:139], v[188:191], v[0:3]
	s_barrier
	s_setprio 0
	s_add_i32 s84, s84, 2
	s_add_u32 s72, s72, 0x100
	s_addc_u32 s73, s73, 0
	s_add_u32 s67, s67, 0x100
	s_addc_u32 s69, s69, 0
	s_cmp_gt_u32 s84, 29
	s_cbranch_scc0 .LBB0_1366
	s_and_b64 vcc, exec, s[30:31]
	s_cbranch_vccz .LBB0_1369
	s_barrier
